# GEMM K-loops: s_setprio 1 issued before the pre-MMA barrier, redundant post-barrier lgkmcnt(0) dropped, s_setprio 0 after the post-MMA barrier (on top of the dattn loop edits)
# speedup vs baseline: 1.0013x; 1.0013x over previous
.LBB0_175:
	ds_read_b128 v[144:147], v151
	ds_read_b128 v[156:159], v151 offset:1024
	ds_read_b128 v[160:163], v151 offset:2048
	ds_read_b128 v[164:167], v151 offset:3072
	ds_read_b128 v[168:171], v152
	ds_read_b128 v[172:175], v152 offset:1024
	ds_read_b128 v[176:179], v152 offset:2048
	ds_read_b128 v[180:183], v152 offset:3072
	s_add_u32 s24, s22, 0xfffc0080
	s_addc_u32 s25, s23, -1
	s_cmp_eq_u32 s90, 12
	s_cselect_b32 s27, s15, s25
	s_cselect_b32 s26, s86, s24
	s_cselect_b32 s25, s13, s89
	s_cselect_b32 s24, s87, s88
	v_lshl_add_u64 v[204:205], s[22:23], 0, v[136:137]
	s_add_i32 m0, s21, 0xc000
	ds_read_b128 v[184:187], v153
	ds_read_b128 v[188:191], v153 offset:1024
	ds_read_b128 v[192:195], v153 offset:2048
	ds_read_b128 v[196:199], v153 offset:3072
	ds_read_b128 v[200:203], v153 offset:4096
	ds_read_b128 v[208:211], v153 offset:5120
	ds_read_b128 v[212:215], v153 offset:6144
	ds_read_b128 v[216:219], v153 offset:7168
	global_load_lds_dwordx4 v[204:205], off
	v_lshl_add_u64 v[204:205], s[22:23], 0, v[138:139]
	s_add_i32 m0, s21, 0xe000
	s_nop 0
	global_load_lds_dwordx4 v[204:205], off
	s_waitcnt vmcnt(8)
	s_waitcnt lgkmcnt(0)
	s_setprio 1
	s_barrier
	v_mfma_f32_16x16x32_bf16 v[124:127], v[144:147], v[184:187], v[124:127]
	v_mfma_f32_16x16x32_bf16 v[120:123], v[160:163], v[184:187], v[120:123]
	v_mfma_f32_16x16x32_bf16 v[116:119], v[144:147], v[192:195], v[116:119]
	v_mfma_f32_16x16x32_bf16 v[112:115], v[160:163], v[192:195], v[112:115]
	v_mfma_f32_16x16x32_bf16 v[104:107], v[144:147], v[200:203], v[104:107]
	v_mfma_f32_16x16x32_bf16 v[96:99], v[160:163], v[200:203], v[96:99]
	v_mfma_f32_16x16x32_bf16 v[76:79], v[144:147], v[212:215], v[76:79]
	v_mfma_f32_16x16x32_bf16 v[72:75], v[160:163], v[212:215], v[72:75]
	v_mfma_f32_16x16x32_bf16 v[124:127], v[156:159], v[188:191], v[124:127]
	v_mfma_f32_16x16x32_bf16 v[120:123], v[164:167], v[188:191], v[120:123]
	v_mfma_f32_16x16x32_bf16 v[116:119], v[156:159], v[196:199], v[116:119]
	v_mfma_f32_16x16x32_bf16 v[112:115], v[164:167], v[196:199], v[112:115]
	v_mfma_f32_16x16x32_bf16 v[104:107], v[156:159], v[208:211], v[104:107]
	v_mfma_f32_16x16x32_bf16 v[96:99], v[164:167], v[208:211], v[96:99]
	v_mfma_f32_16x16x32_bf16 v[76:79], v[156:159], v[216:219], v[76:79]
	v_mfma_f32_16x16x32_bf16 v[72:75], v[164:167], v[216:219], v[72:75]
	s_setprio 0
	s_setprio 1
	v_mfma_f32_16x16x32_bf16 v[108:111], v[168:171], v[184:187], v[108:111]
	v_mfma_f32_16x16x32_bf16 v[100:103], v[176:179], v[184:187], v[100:103]
	v_mfma_f32_16x16x32_bf16 v[92:95], v[168:171], v[192:195], v[92:95]
	v_mfma_f32_16x16x32_bf16 v[88:91], v[176:179], v[192:195], v[88:91]
	v_mfma_f32_16x16x32_bf16 v[84:87], v[168:171], v[200:203], v[84:87]
	v_mfma_f32_16x16x32_bf16 v[80:83], v[176:179], v[200:203], v[80:83]
	v_mfma_f32_16x16x32_bf16 v[68:71], v[168:171], v[212:215], v[68:71]
	v_mfma_f32_16x16x32_bf16 v[64:67], v[176:179], v[212:215], v[64:67]
	v_mfma_f32_16x16x32_bf16 v[108:111], v[172:175], v[188:191], v[108:111]
	v_mfma_f32_16x16x32_bf16 v[100:103], v[180:183], v[188:191], v[100:103]
	v_mfma_f32_16x16x32_bf16 v[92:95], v[172:175], v[196:199], v[92:95]
	v_mfma_f32_16x16x32_bf16 v[88:91], v[180:183], v[196:199], v[88:91]
	v_mfma_f32_16x16x32_bf16 v[84:87], v[172:175], v[208:211], v[84:87]
	v_mfma_f32_16x16x32_bf16 v[80:83], v[180:183], v[208:211], v[80:83]
	v_mfma_f32_16x16x32_bf16 v[68:71], v[172:175], v[216:219], v[68:71]
	v_mfma_f32_16x16x32_bf16 v[64:67], v[180:183], v[216:219], v[64:67]
	s_barrier
	s_setprio 0
	s_add_i32 s91, s79, s30
	v_lshl_add_u64 v[204:205], s[24:25], 0, v[132:133]
	s_mov_b32 m0, s91
	ds_read_b128 v[184:187], v153 offset:16384
	ds_read_b128 v[188:191], v153 offset:17408
	ds_read_b128 v[192:195], v153 offset:18432
	ds_read_b128 v[196:199], v153 offset:19456
	ds_read_b128 v[200:203], v153 offset:20480
	ds_read_b128 v[208:211], v153 offset:21504
	ds_read_b128 v[212:215], v153 offset:22528
	ds_read_b128 v[216:219], v153 offset:23552
	global_load_lds_dwordx4 v[204:205], off
	s_add_i32 m0, s91, 0x2000
	s_add_u32 s92, s24, 0x40000
	v_lshl_add_u64 v[220:221], s[24:25], 0, v[128:129]
	s_addc_u32 s93, s25, 0
	s_add_i32 s91, s84, s30
	global_load_lds_dwordx4 v[220:221], off
	v_lshl_add_u64 v[222:223], s[92:93], 0, v[132:133]
	s_mov_b32 m0, s91
	v_lshl_add_u64 v[224:225], s[26:27], 0, v[130:131]
	global_load_lds_dwordx4 v[222:223], off
	v_lshl_add_u64 v[222:223], s[92:93], 0, v[128:129]
	s_add_i32 m0, s91, 0x2000
	s_nop 0
	global_load_lds_dwordx4 v[222:223], off
	v_lshl_add_u64 v[222:223], s[26:27], 0, v[134:135]
	s_mov_b32 m0, s21
	s_nop 0
	global_load_lds_dwordx4 v[222:223], off
	s_mov_b32 m0, s35
	s_nop 0
	global_load_lds_dwordx4 v[224:225], off
	s_waitcnt vmcnt(8)
	s_waitcnt lgkmcnt(0)
	s_setprio 1
	s_barrier
	v_mfma_f32_16x16x32_bf16 v[60:63], v[144:147], v[184:187], v[60:63]
	v_mfma_f32_16x16x32_bf16 v[56:59], v[160:163], v[184:187], v[56:59]
	v_mfma_f32_16x16x32_bf16 v[44:47], v[144:147], v[192:195], v[44:47]
	v_mfma_f32_16x16x32_bf16 v[40:43], v[160:163], v[192:195], v[40:43]
	v_mfma_f32_16x16x32_bf16 v[28:31], v[144:147], v[200:203], v[28:31]
	v_mfma_f32_16x16x32_bf16 v[24:27], v[160:163], v[200:203], v[24:27]
	v_mfma_f32_16x16x32_bf16 v[12:15], v[144:147], v[212:215], v[12:15]
	v_mfma_f32_16x16x32_bf16 v[8:11], v[160:163], v[212:215], v[8:11]
	v_mfma_f32_16x16x32_bf16 v[60:63], v[156:159], v[188:191], v[60:63]
	v_mfma_f32_16x16x32_bf16 v[56:59], v[164:167], v[188:191], v[56:59]
	v_mfma_f32_16x16x32_bf16 v[44:47], v[156:159], v[196:199], v[44:47]
	v_mfma_f32_16x16x32_bf16 v[40:43], v[164:167], v[196:199], v[40:43]
	v_mfma_f32_16x16x32_bf16 v[28:31], v[156:159], v[208:211], v[28:31]
	v_mfma_f32_16x16x32_bf16 v[24:27], v[164:167], v[208:211], v[24:27]
	v_mfma_f32_16x16x32_bf16 v[12:15], v[156:159], v[216:219], v[12:15]
	v_mfma_f32_16x16x32_bf16 v[8:11], v[164:167], v[216:219], v[8:11]
	s_setprio 0
	s_setprio 1
	v_mfma_f32_16x16x32_bf16 v[52:55], v[168:171], v[184:187], v[52:55]
	v_mfma_f32_16x16x32_bf16 v[48:51], v[176:179], v[184:187], v[48:51]
	v_mfma_f32_16x16x32_bf16 v[36:39], v[168:171], v[192:195], v[36:39]
	v_mfma_f32_16x16x32_bf16 v[32:35], v[176:179], v[192:195], v[32:35]
	v_mfma_f32_16x16x32_bf16 v[20:23], v[168:171], v[200:203], v[20:23]
	v_mfma_f32_16x16x32_bf16 v[16:19], v[176:179], v[200:203], v[16:19]
	v_mfma_f32_16x16x32_bf16 v[4:7], v[168:171], v[212:215], v[4:7]
	v_mfma_f32_16x16x32_bf16 v[0:3], v[176:179], v[212:215], v[0:3]
	v_mfma_f32_16x16x32_bf16 v[52:55], v[172:175], v[188:191], v[52:55]
	v_mfma_f32_16x16x32_bf16 v[48:51], v[180:183], v[188:191], v[48:51]
	v_mfma_f32_16x16x32_bf16 v[36:39], v[172:175], v[196:199], v[36:39]
	v_mfma_f32_16x16x32_bf16 v[32:35], v[180:183], v[196:199], v[32:35]
	v_mfma_f32_16x16x32_bf16 v[20:23], v[172:175], v[208:211], v[20:23]
	v_mfma_f32_16x16x32_bf16 v[16:19], v[180:183], v[208:211], v[16:19]
	v_mfma_f32_16x16x32_bf16 v[4:7], v[172:175], v[216:219], v[4:7]
	v_mfma_f32_16x16x32_bf16 v[0:3], v[180:183], v[216:219], v[0:3]
	s_barrier
	s_setprio 0
	s_add_i32 s91, 0, 0x18000
	s_add_i32 s92, 0, 0x1c000
	v_add_u32_e32 v164, s91, v149
	v_add_u32_e32 v180, s92, v149
	ds_read_b128 v[144:147], v164
	ds_read_b128 v[156:159], v164 offset:1024
	ds_read_b128 v[160:163], v164 offset:2048
	ds_read_b128 v[164:167], v164 offset:3072
	ds_read_b128 v[168:171], v180
	ds_read_b128 v[172:175], v180 offset:1024
	ds_read_b128 v[176:179], v180 offset:2048
	ds_read_b128 v[180:183], v180 offset:3072
	s_add_u32 s26, s26, 0x40000
	s_addc_u32 s27, s27, 0
	s_mov_b32 m0, s36
	v_lshl_add_u64 v[226:227], s[26:27], 0, v[134:135]
	ds_read_b128 v[184:187], v153 offset:32768
	ds_read_b128 v[188:191], v153 offset:33792
	ds_read_b128 v[192:195], v153 offset:34816
	ds_read_b128 v[196:199], v153 offset:35840
	ds_read_b128 v[200:203], v153 offset:36864
	ds_read_b128 v[208:211], v153 offset:37888
	ds_read_b128 v[212:215], v153 offset:38912
	ds_read_b128 v[216:219], v153 offset:39936
	global_load_lds_dwordx4 v[226:227], off
	v_lshl_add_u64 v[226:227], s[26:27], 0, v[130:131]
	s_mov_b32 m0, s37
	s_nop 0
	global_load_lds_dwordx4 v[226:227], off
	s_waitcnt vmcnt(8)
	s_waitcnt lgkmcnt(0)
	s_setprio 1
	s_barrier
	v_mfma_f32_16x16x32_bf16 v[124:127], v[144:147], v[184:187], v[124:127]
	v_mfma_f32_16x16x32_bf16 v[120:123], v[160:163], v[184:187], v[120:123]
	v_mfma_f32_16x16x32_bf16 v[116:119], v[144:147], v[192:195], v[116:119]
	v_mfma_f32_16x16x32_bf16 v[112:115], v[160:163], v[192:195], v[112:115]
	v_mfma_f32_16x16x32_bf16 v[104:107], v[144:147], v[200:203], v[104:107]
	v_mfma_f32_16x16x32_bf16 v[96:99], v[160:163], v[200:203], v[96:99]
	v_mfma_f32_16x16x32_bf16 v[76:79], v[144:147], v[212:215], v[76:79]
	v_mfma_f32_16x16x32_bf16 v[72:75], v[160:163], v[212:215], v[72:75]
	v_mfma_f32_16x16x32_bf16 v[124:127], v[156:159], v[188:191], v[124:127]
	v_mfma_f32_16x16x32_bf16 v[120:123], v[164:167], v[188:191], v[120:123]
	v_mfma_f32_16x16x32_bf16 v[116:119], v[156:159], v[196:199], v[116:119]
	v_mfma_f32_16x16x32_bf16 v[112:115], v[164:167], v[196:199], v[112:115]
	v_mfma_f32_16x16x32_bf16 v[104:107], v[156:159], v[208:211], v[104:107]
	v_mfma_f32_16x16x32_bf16 v[96:99], v[164:167], v[208:211], v[96:99]
	v_mfma_f32_16x16x32_bf16 v[76:79], v[156:159], v[216:219], v[76:79]
	v_mfma_f32_16x16x32_bf16 v[72:75], v[164:167], v[216:219], v[72:75]
	s_setprio 0
	s_setprio 1
	v_mfma_f32_16x16x32_bf16 v[108:111], v[168:171], v[184:187], v[108:111]
	v_mfma_f32_16x16x32_bf16 v[100:103], v[176:179], v[184:187], v[100:103]
	v_mfma_f32_16x16x32_bf16 v[92:95], v[168:171], v[192:195], v[92:95]
	v_mfma_f32_16x16x32_bf16 v[88:91], v[176:179], v[192:195], v[88:91]
	v_mfma_f32_16x16x32_bf16 v[84:87], v[168:171], v[200:203], v[84:87]
	v_mfma_f32_16x16x32_bf16 v[80:83], v[176:179], v[200:203], v[80:83]
	v_mfma_f32_16x16x32_bf16 v[68:71], v[168:171], v[212:215], v[68:71]
	v_mfma_f32_16x16x32_bf16 v[64:67], v[176:179], v[212:215], v[64:67]
	v_mfma_f32_16x16x32_bf16 v[108:111], v[172:175], v[188:191], v[108:111]
	v_mfma_f32_16x16x32_bf16 v[100:103], v[180:183], v[188:191], v[100:103]
	v_mfma_f32_16x16x32_bf16 v[92:95], v[172:175], v[196:199], v[92:95]
	v_mfma_f32_16x16x32_bf16 v[88:91], v[180:183], v[196:199], v[88:91]
	v_mfma_f32_16x16x32_bf16 v[84:87], v[172:175], v[208:211], v[84:87]
	v_mfma_f32_16x16x32_bf16 v[80:83], v[180:183], v[208:211], v[80:83]
	v_mfma_f32_16x16x32_bf16 v[68:71], v[172:175], v[216:219], v[68:71]
	v_mfma_f32_16x16x32_bf16 v[64:67], v[180:183], v[216:219], v[64:67]
	s_barrier
	s_setprio 0
	s_add_i32 s26, s91, s30
	v_lshl_add_u64 v[204:205], v[204:205], 0, s[8:9]
	s_mov_b32 m0, s26
	ds_read_b128 v[184:187], v153 offset:49152
	ds_read_b128 v[188:191], v153 offset:50176
	ds_read_b128 v[192:195], v153 offset:51200
	ds_read_b128 v[196:199], v153 offset:52224
	ds_read_b128 v[200:203], v153 offset:53248
	ds_read_b128 v[208:211], v153 offset:54272
	ds_read_b128 v[212:215], v153 offset:55296
	ds_read_b128 v[216:219], v153 offset:56320
	global_load_lds_dwordx4 v[204:205], off
	s_add_i32 m0, s26, 0x2000
	s_add_u32 s24, s24, 0x40080
	v_lshl_add_u64 v[204:205], v[220:221], 0, s[8:9]
	s_addc_u32 s25, s25, 0
	s_add_i32 s26, s92, s30
	global_load_lds_dwordx4 v[204:205], off
	v_lshl_add_u64 v[204:205], s[24:25], 0, v[132:133]
	s_mov_b32 m0, s26
	s_nop 0
	global_load_lds_dwordx4 v[204:205], off
	v_lshl_add_u64 v[204:205], s[24:25], 0, v[128:129]
	s_add_i32 m0, s26, 0x2000
	s_nop 0
	global_load_lds_dwordx4 v[204:205], off
	v_lshl_add_u64 v[204:205], v[222:223], 0, s[8:9]
	s_mov_b32 m0, s76
	s_nop 0
	global_load_lds_dwordx4 v[204:205], off
	v_lshl_add_u64 v[204:205], v[224:225], 0, s[8:9]
	s_mov_b32 m0, s77
	s_nop 0
	global_load_lds_dwordx4 v[204:205], off
	s_waitcnt vmcnt(8)
	s_waitcnt lgkmcnt(0)
	s_setprio 1
	s_barrier
	v_mfma_f32_16x16x32_bf16 v[60:63], v[144:147], v[184:187], v[60:63]
	v_mfma_f32_16x16x32_bf16 v[56:59], v[160:163], v[184:187], v[56:59]
	v_mfma_f32_16x16x32_bf16 v[44:47], v[144:147], v[192:195], v[44:47]
	v_mfma_f32_16x16x32_bf16 v[40:43], v[160:163], v[192:195], v[40:43]
	v_mfma_f32_16x16x32_bf16 v[28:31], v[144:147], v[200:203], v[28:31]
	v_mfma_f32_16x16x32_bf16 v[24:27], v[160:163], v[200:203], v[24:27]
	v_mfma_f32_16x16x32_bf16 v[12:15], v[144:147], v[212:215], v[12:15]
	v_mfma_f32_16x16x32_bf16 v[8:11], v[160:163], v[212:215], v[8:11]
	v_mfma_f32_16x16x32_bf16 v[60:63], v[156:159], v[188:191], v[60:63]
	v_mfma_f32_16x16x32_bf16 v[56:59], v[164:167], v[188:191], v[56:59]
	v_mfma_f32_16x16x32_bf16 v[44:47], v[156:159], v[196:199], v[44:47]
	v_mfma_f32_16x16x32_bf16 v[40:43], v[164:167], v[196:199], v[40:43]
	v_mfma_f32_16x16x32_bf16 v[28:31], v[156:159], v[208:211], v[28:31]
	v_mfma_f32_16x16x32_bf16 v[24:27], v[164:167], v[208:211], v[24:27]
	v_mfma_f32_16x16x32_bf16 v[12:15], v[156:159], v[216:219], v[12:15]
	v_mfma_f32_16x16x32_bf16 v[8:11], v[164:167], v[216:219], v[8:11]
	s_setprio 0
	s_setprio 1
	v_mfma_f32_16x16x32_bf16 v[52:55], v[168:171], v[184:187], v[52:55]
	v_mfma_f32_16x16x32_bf16 v[48:51], v[176:179], v[184:187], v[48:51]
	v_mfma_f32_16x16x32_bf16 v[36:39], v[168:171], v[192:195], v[36:39]
	v_mfma_f32_16x16x32_bf16 v[32:35], v[176:179], v[192:195], v[32:35]
	v_mfma_f32_16x16x32_bf16 v[20:23], v[168:171], v[200:203], v[20:23]
	v_mfma_f32_16x16x32_bf16 v[16:19], v[176:179], v[200:203], v[16:19]
	v_mfma_f32_16x16x32_bf16 v[4:7], v[168:171], v[212:215], v[4:7]
	v_mfma_f32_16x16x32_bf16 v[0:3], v[176:179], v[212:215], v[0:3]
	v_mfma_f32_16x16x32_bf16 v[52:55], v[172:175], v[188:191], v[52:55]
	v_mfma_f32_16x16x32_bf16 v[48:51], v[180:183], v[188:191], v[48:51]
	v_mfma_f32_16x16x32_bf16 v[36:39], v[172:175], v[196:199], v[36:39]
	v_mfma_f32_16x16x32_bf16 v[32:35], v[180:183], v[196:199], v[32:35]
	v_mfma_f32_16x16x32_bf16 v[20:23], v[172:175], v[208:211], v[20:23]
	v_mfma_f32_16x16x32_bf16 v[16:19], v[180:183], v[208:211], v[16:19]
	v_mfma_f32_16x16x32_bf16 v[4:7], v[172:175], v[216:219], v[4:7]
	v_mfma_f32_16x16x32_bf16 v[0:3], v[180:183], v[216:219], v[0:3]
	s_barrier
	s_setprio 0
	s_add_i32 s90, s90, 2
	s_add_u32 s22, s22, 0x100
	s_addc_u32 s23, s23, 0
	s_add_u32 s88, s88, 0x100
	s_addc_u32 s89, s89, 0
	s_cmp_gt_u32 s90, 13
	s_cbranch_scc0 .LBB0_175
	s_and_b64 vcc, exec, s[10:11]
	s_cbranch_vccz .LBB0_178
	s_barrier

.LBB0_199:
	ds_read_b128 v[144:147], v167
	ds_read_b128 v[148:151], v167 offset:1024
	ds_read_b128 v[152:155], v167 offset:2048
	ds_read_b128 v[156:159], v167 offset:3072
	ds_read_b128 v[160:163], v168
	ds_read_b128 v[172:175], v168 offset:1024
	ds_read_b128 v[176:179], v168 offset:2048
	ds_read_b128 v[180:183], v168 offset:3072
	s_add_u32 s24, s22, 0xfffc0080
	s_addc_u32 s25, s23, -1
	s_cmp_eq_u32 s92, 12
	s_cselect_b32 s27, s15, s25
	s_cselect_b32 s26, s88, s24
	s_cselect_b32 s25, s13, s91
	s_cselect_b32 s24, s89, s90
	v_lshl_add_u64 v[204:205], s[22:23], 0, v[136:137]
	s_add_i32 m0, s21, 0xc000
	ds_read_b128 v[184:187], v169
	ds_read_b128 v[188:191], v169 offset:1024
	ds_read_b128 v[192:195], v169 offset:2048
	ds_read_b128 v[196:199], v169 offset:3072
	ds_read_b128 v[200:203], v169 offset:4096
	ds_read_b128 v[208:211], v169 offset:5120
	ds_read_b128 v[212:215], v169 offset:6144
	ds_read_b128 v[216:219], v169 offset:7168
	global_load_lds_dwordx4 v[204:205], off
	v_lshl_add_u64 v[204:205], s[22:23], 0, v[138:139]
	s_add_i32 m0, s21, 0xe000
	s_nop 0
	global_load_lds_dwordx4 v[204:205], off
	s_waitcnt vmcnt(8)
	s_waitcnt lgkmcnt(0)
	s_setprio 1
	s_barrier
	v_mfma_f32_16x16x32_bf16 v[124:127], v[144:147], v[184:187], v[124:127]
	v_mfma_f32_16x16x32_bf16 v[120:123], v[152:155], v[184:187], v[120:123]
	v_mfma_f32_16x16x32_bf16 v[116:119], v[144:147], v[192:195], v[116:119]
	v_mfma_f32_16x16x32_bf16 v[112:115], v[152:155], v[192:195], v[112:115]
	v_mfma_f32_16x16x32_bf16 v[108:111], v[144:147], v[200:203], v[108:111]
	v_mfma_f32_16x16x32_bf16 v[88:91], v[152:155], v[200:203], v[88:91]
	v_mfma_f32_16x16x32_bf16 v[80:83], v[144:147], v[212:215], v[80:83]
	v_mfma_f32_16x16x32_bf16 v[72:75], v[152:155], v[212:215], v[72:75]
	v_mfma_f32_16x16x32_bf16 v[124:127], v[148:151], v[188:191], v[124:127]
	v_mfma_f32_16x16x32_bf16 v[120:123], v[156:159], v[188:191], v[120:123]
	v_mfma_f32_16x16x32_bf16 v[116:119], v[148:151], v[196:199], v[116:119]
	v_mfma_f32_16x16x32_bf16 v[112:115], v[156:159], v[196:199], v[112:115]
	v_mfma_f32_16x16x32_bf16 v[108:111], v[148:151], v[208:211], v[108:111]
	v_mfma_f32_16x16x32_bf16 v[88:91], v[156:159], v[208:211], v[88:91]
	v_mfma_f32_16x16x32_bf16 v[80:83], v[148:151], v[216:219], v[80:83]
	v_mfma_f32_16x16x32_bf16 v[72:75], v[156:159], v[216:219], v[72:75]
	s_setprio 0
	s_setprio 1
	v_mfma_f32_16x16x32_bf16 v[104:107], v[160:163], v[184:187], v[104:107]
	v_mfma_f32_16x16x32_bf16 v[100:103], v[176:179], v[184:187], v[100:103]
	v_mfma_f32_16x16x32_bf16 v[96:99], v[160:163], v[192:195], v[96:99]
	v_mfma_f32_16x16x32_bf16 v[92:95], v[176:179], v[192:195], v[92:95]
	v_mfma_f32_16x16x32_bf16 v[84:87], v[160:163], v[200:203], v[84:87]
	v_mfma_f32_16x16x32_bf16 v[76:79], v[176:179], v[200:203], v[76:79]
	v_mfma_f32_16x16x32_bf16 v[68:71], v[160:163], v[212:215], v[68:71]
	v_mfma_f32_16x16x32_bf16 v[64:67], v[176:179], v[212:215], v[64:67]
	v_mfma_f32_16x16x32_bf16 v[104:107], v[172:175], v[188:191], v[104:107]
	v_mfma_f32_16x16x32_bf16 v[100:103], v[180:183], v[188:191], v[100:103]
	v_mfma_f32_16x16x32_bf16 v[96:99], v[172:175], v[196:199], v[96:99]
	v_mfma_f32_16x16x32_bf16 v[92:95], v[180:183], v[196:199], v[92:95]
	v_mfma_f32_16x16x32_bf16 v[84:87], v[172:175], v[208:211], v[84:87]
	v_mfma_f32_16x16x32_bf16 v[76:79], v[180:183], v[208:211], v[76:79]
	v_mfma_f32_16x16x32_bf16 v[68:71], v[172:175], v[216:219], v[68:71]
	v_mfma_f32_16x16x32_bf16 v[64:67], v[180:183], v[216:219], v[64:67]
	s_barrier
	s_setprio 0
	s_add_i32 s93, s84, s35
	v_lshl_add_u64 v[204:205], s[24:25], 0, v[130:131]
	s_mov_b32 m0, s93
	ds_read_b128 v[184:187], v169 offset:16384
	ds_read_b128 v[188:191], v169 offset:17408
	ds_read_b128 v[192:195], v169 offset:18432
	ds_read_b128 v[196:199], v169 offset:19456
	ds_read_b128 v[200:203], v169 offset:20480
	ds_read_b128 v[208:211], v169 offset:21504
	ds_read_b128 v[212:215], v169 offset:22528
	ds_read_b128 v[216:219], v169 offset:23552
	global_load_lds_dwordx4 v[204:205], off
	s_add_i32 m0, s93, 0x2000
	s_add_u32 s94, s24, 0x40000
	v_lshl_add_u64 v[220:221], s[24:25], 0, v[134:135]
	s_addc_u32 s95, s25, 0
	s_add_i32 s93, s85, s35
	global_load_lds_dwordx4 v[220:221], off
	v_lshl_add_u64 v[222:223], s[94:95], 0, v[130:131]
	s_mov_b32 m0, s93
	v_lshl_add_u64 v[224:225], s[26:27], 0, v[132:133]
	global_load_lds_dwordx4 v[222:223], off
	v_lshl_add_u64 v[222:223], s[94:95], 0, v[134:135]
	s_add_i32 m0, s93, 0x2000
	s_nop 0
	global_load_lds_dwordx4 v[222:223], off
	v_lshl_add_u64 v[222:223], s[26:27], 0, v[128:129]
	s_mov_b32 m0, s21
	s_nop 0
	global_load_lds_dwordx4 v[222:223], off
	s_mov_b32 m0, s36
	s_nop 0
	global_load_lds_dwordx4 v[224:225], off
	s_waitcnt vmcnt(8)
	s_waitcnt lgkmcnt(0)
	s_setprio 1
	s_barrier
	v_mfma_f32_16x16x32_bf16 v[60:63], v[144:147], v[184:187], v[60:63]
	v_mfma_f32_16x16x32_bf16 v[56:59], v[152:155], v[184:187], v[56:59]
	v_mfma_f32_16x16x32_bf16 v[48:51], v[144:147], v[192:195], v[48:51]
	v_mfma_f32_16x16x32_bf16 v[40:43], v[152:155], v[192:195], v[40:43]
	v_mfma_f32_16x16x32_bf16 v[32:35], v[144:147], v[200:203], v[32:35]
	v_mfma_f32_16x16x32_bf16 v[24:27], v[152:155], v[200:203], v[24:27]
	v_mfma_f32_16x16x32_bf16 v[16:19], v[144:147], v[212:215], v[16:19]
	v_mfma_f32_16x16x32_bf16 v[8:11], v[152:155], v[212:215], v[8:11]
	v_mfma_f32_16x16x32_bf16 v[60:63], v[148:151], v[188:191], v[60:63]
	v_mfma_f32_16x16x32_bf16 v[56:59], v[156:159], v[188:191], v[56:59]
	v_mfma_f32_16x16x32_bf16 v[48:51], v[148:151], v[196:199], v[48:51]
	v_mfma_f32_16x16x32_bf16 v[40:43], v[156:159], v[196:199], v[40:43]
	v_mfma_f32_16x16x32_bf16 v[32:35], v[148:151], v[208:211], v[32:35]
	v_mfma_f32_16x16x32_bf16 v[24:27], v[156:159], v[208:211], v[24:27]
	v_mfma_f32_16x16x32_bf16 v[16:19], v[148:151], v[216:219], v[16:19]
	v_mfma_f32_16x16x32_bf16 v[8:11], v[156:159], v[216:219], v[8:11]
	s_setprio 0
	s_setprio 1
	v_mfma_f32_16x16x32_bf16 v[52:55], v[160:163], v[184:187], v[52:55]
	v_mfma_f32_16x16x32_bf16 v[44:47], v[176:179], v[184:187], v[44:47]
	v_mfma_f32_16x16x32_bf16 v[36:39], v[160:163], v[192:195], v[36:39]
	v_mfma_f32_16x16x32_bf16 v[28:31], v[176:179], v[192:195], v[28:31]
	v_mfma_f32_16x16x32_bf16 v[20:23], v[160:163], v[200:203], v[20:23]
	v_mfma_f32_16x16x32_bf16 v[12:15], v[176:179], v[200:203], v[12:15]
	v_mfma_f32_16x16x32_bf16 v[4:7], v[160:163], v[212:215], v[4:7]
	v_mfma_f32_16x16x32_bf16 v[0:3], v[176:179], v[212:215], v[0:3]
	v_mfma_f32_16x16x32_bf16 v[52:55], v[172:175], v[188:191], v[52:55]
	v_mfma_f32_16x16x32_bf16 v[44:47], v[180:183], v[188:191], v[44:47]
	v_mfma_f32_16x16x32_bf16 v[36:39], v[172:175], v[196:199], v[36:39]
	v_mfma_f32_16x16x32_bf16 v[28:31], v[180:183], v[196:199], v[28:31]
	v_mfma_f32_16x16x32_bf16 v[20:23], v[172:175], v[208:211], v[20:23]
	v_mfma_f32_16x16x32_bf16 v[12:15], v[180:183], v[208:211], v[12:15]
	v_mfma_f32_16x16x32_bf16 v[4:7], v[172:175], v[216:219], v[4:7]
	v_mfma_f32_16x16x32_bf16 v[0:3], v[180:183], v[216:219], v[0:3]
	s_barrier
	s_setprio 0
	s_add_i32 s93, 0, 0x18000
	s_add_i32 s94, 0, 0x1c000
	v_add_u32_e32 v156, s93, v165
	v_add_u32_e32 v171, s94, v165
	ds_read_b128 v[144:147], v156
	ds_read_b128 v[148:151], v156 offset:1024
	ds_read_b128 v[152:155], v156 offset:2048
	ds_read_b128 v[156:159], v156 offset:3072
	ds_read_b128 v[160:163], v171
	ds_read_b128 v[172:175], v171 offset:1024
	ds_read_b128 v[176:179], v171 offset:2048
	ds_read_b128 v[180:183], v171 offset:3072
	s_add_u32 s26, s26, 0x40000
	s_addc_u32 s27, s27, 0
	s_mov_b32 m0, s37
	v_lshl_add_u64 v[226:227], s[26:27], 0, v[128:129]
	ds_read_b128 v[184:187], v169 offset:32768
	ds_read_b128 v[188:191], v169 offset:33792
	ds_read_b128 v[192:195], v169 offset:34816
	ds_read_b128 v[196:199], v169 offset:35840
	ds_read_b128 v[200:203], v169 offset:36864
	ds_read_b128 v[208:211], v169 offset:37888
	ds_read_b128 v[212:215], v169 offset:38912
	ds_read_b128 v[216:219], v169 offset:39936
	global_load_lds_dwordx4 v[226:227], off
	v_lshl_add_u64 v[226:227], s[26:27], 0, v[132:133]
	s_mov_b32 m0, s39
	s_nop 0
	global_load_lds_dwordx4 v[226:227], off
	s_waitcnt vmcnt(8)
	s_waitcnt lgkmcnt(0)
	s_setprio 1
	s_barrier
	v_mfma_f32_16x16x32_bf16 v[124:127], v[144:147], v[184:187], v[124:127]
	v_mfma_f32_16x16x32_bf16 v[120:123], v[152:155], v[184:187], v[120:123]
	v_mfma_f32_16x16x32_bf16 v[116:119], v[144:147], v[192:195], v[116:119]
	v_mfma_f32_16x16x32_bf16 v[112:115], v[152:155], v[192:195], v[112:115]
	v_mfma_f32_16x16x32_bf16 v[108:111], v[144:147], v[200:203], v[108:111]
	v_mfma_f32_16x16x32_bf16 v[88:91], v[152:155], v[200:203], v[88:91]
	v_mfma_f32_16x16x32_bf16 v[80:83], v[144:147], v[212:215], v[80:83]
	v_mfma_f32_16x16x32_bf16 v[72:75], v[152:155], v[212:215], v[72:75]
	v_mfma_f32_16x16x32_bf16 v[124:127], v[148:151], v[188:191], v[124:127]
	v_mfma_f32_16x16x32_bf16 v[120:123], v[156:159], v[188:191], v[120:123]
	v_mfma_f32_16x16x32_bf16 v[116:119], v[148:151], v[196:199], v[116:119]
	v_mfma_f32_16x16x32_bf16 v[112:115], v[156:159], v[196:199], v[112:115]
	v_mfma_f32_16x16x32_bf16 v[108:111], v[148:151], v[208:211], v[108:111]
	v_mfma_f32_16x16x32_bf16 v[88:91], v[156:159], v[208:211], v[88:91]
	v_mfma_f32_16x16x32_bf16 v[80:83], v[148:151], v[216:219], v[80:83]
	v_mfma_f32_16x16x32_bf16 v[72:75], v[156:159], v[216:219], v[72:75]
	s_setprio 0
	s_setprio 1
	v_mfma_f32_16x16x32_bf16 v[104:107], v[160:163], v[184:187], v[104:107]
	v_mfma_f32_16x16x32_bf16 v[100:103], v[176:179], v[184:187], v[100:103]
	v_mfma_f32_16x16x32_bf16 v[96:99], v[160:163], v[192:195], v[96:99]
	v_mfma_f32_16x16x32_bf16 v[92:95], v[176:179], v[192:195], v[92:95]
	v_mfma_f32_16x16x32_bf16 v[84:87], v[160:163], v[200:203], v[84:87]
	v_mfma_f32_16x16x32_bf16 v[76:79], v[176:179], v[200:203], v[76:79]
	v_mfma_f32_16x16x32_bf16 v[68:71], v[160:163], v[212:215], v[68:71]
	v_mfma_f32_16x16x32_bf16 v[64:67], v[176:179], v[212:215], v[64:67]
	v_mfma_f32_16x16x32_bf16 v[104:107], v[172:175], v[188:191], v[104:107]
	v_mfma_f32_16x16x32_bf16 v[100:103], v[180:183], v[188:191], v[100:103]
	v_mfma_f32_16x16x32_bf16 v[96:99], v[172:175], v[196:199], v[96:99]
	v_mfma_f32_16x16x32_bf16 v[92:95], v[180:183], v[196:199], v[92:95]
	v_mfma_f32_16x16x32_bf16 v[84:87], v[172:175], v[208:211], v[84:87]
	v_mfma_f32_16x16x32_bf16 v[76:79], v[180:183], v[208:211], v[76:79]
	v_mfma_f32_16x16x32_bf16 v[68:71], v[172:175], v[216:219], v[68:71]
	v_mfma_f32_16x16x32_bf16 v[64:67], v[180:183], v[216:219], v[64:67]
	s_barrier
	s_setprio 0
	s_add_i32 s26, s93, s35
	v_lshl_add_u64 v[204:205], v[204:205], 0, s[8:9]
	s_mov_b32 m0, s26
	ds_read_b128 v[184:187], v169 offset:49152
	ds_read_b128 v[188:191], v169 offset:50176
	ds_read_b128 v[192:195], v169 offset:51200
	ds_read_b128 v[196:199], v169 offset:52224
	ds_read_b128 v[200:203], v169 offset:53248
	ds_read_b128 v[208:211], v169 offset:54272
	ds_read_b128 v[212:215], v169 offset:55296
	ds_read_b128 v[216:219], v169 offset:56320
	global_load_lds_dwordx4 v[204:205], off
	s_add_i32 m0, s26, 0x2000
	s_add_u32 s24, s24, 0x40080
	v_lshl_add_u64 v[204:205], v[220:221], 0, s[8:9]
	s_addc_u32 s25, s25, 0
	s_add_i32 s26, s94, s35
	global_load_lds_dwordx4 v[204:205], off
	v_lshl_add_u64 v[204:205], s[24:25], 0, v[130:131]
	s_mov_b32 m0, s26
	s_nop 0
	global_load_lds_dwordx4 v[204:205], off
	v_lshl_add_u64 v[204:205], s[24:25], 0, v[134:135]
	s_add_i32 m0, s26, 0x2000
	s_nop 0
	global_load_lds_dwordx4 v[204:205], off
	v_lshl_add_u64 v[204:205], v[222:223], 0, s[8:9]
	s_mov_b32 m0, s77
	s_nop 0
	global_load_lds_dwordx4 v[204:205], off
	v_lshl_add_u64 v[204:205], v[224:225], 0, s[8:9]
	s_mov_b32 m0, s78
	s_nop 0
	global_load_lds_dwordx4 v[204:205], off
	s_waitcnt vmcnt(8)
	s_waitcnt lgkmcnt(0)
	s_setprio 1
	s_barrier
	v_mfma_f32_16x16x32_bf16 v[60:63], v[144:147], v[184:187], v[60:63]
	v_mfma_f32_16x16x32_bf16 v[56:59], v[152:155], v[184:187], v[56:59]
	v_mfma_f32_16x16x32_bf16 v[48:51], v[144:147], v[192:195], v[48:51]
	v_mfma_f32_16x16x32_bf16 v[40:43], v[152:155], v[192:195], v[40:43]
	v_mfma_f32_16x16x32_bf16 v[32:35], v[144:147], v[200:203], v[32:35]
	v_mfma_f32_16x16x32_bf16 v[24:27], v[152:155], v[200:203], v[24:27]
	v_mfma_f32_16x16x32_bf16 v[16:19], v[144:147], v[212:215], v[16:19]
	v_mfma_f32_16x16x32_bf16 v[8:11], v[152:155], v[212:215], v[8:11]
	v_mfma_f32_16x16x32_bf16 v[60:63], v[148:151], v[188:191], v[60:63]
	v_mfma_f32_16x16x32_bf16 v[56:59], v[156:159], v[188:191], v[56:59]
	v_mfma_f32_16x16x32_bf16 v[48:51], v[148:151], v[196:199], v[48:51]
	v_mfma_f32_16x16x32_bf16 v[40:43], v[156:159], v[196:199], v[40:43]
	v_mfma_f32_16x16x32_bf16 v[32:35], v[148:151], v[208:211], v[32:35]
	v_mfma_f32_16x16x32_bf16 v[24:27], v[156:159], v[208:211], v[24:27]
	v_mfma_f32_16x16x32_bf16 v[16:19], v[148:151], v[216:219], v[16:19]
	v_mfma_f32_16x16x32_bf16 v[8:11], v[156:159], v[216:219], v[8:11]
	s_setprio 0
	s_setprio 1
	v_mfma_f32_16x16x32_bf16 v[52:55], v[160:163], v[184:187], v[52:55]
	v_mfma_f32_16x16x32_bf16 v[44:47], v[176:179], v[184:187], v[44:47]
	v_mfma_f32_16x16x32_bf16 v[36:39], v[160:163], v[192:195], v[36:39]
	v_mfma_f32_16x16x32_bf16 v[28:31], v[176:179], v[192:195], v[28:31]
	v_mfma_f32_16x16x32_bf16 v[20:23], v[160:163], v[200:203], v[20:23]
	v_mfma_f32_16x16x32_bf16 v[12:15], v[176:179], v[200:203], v[12:15]
	v_mfma_f32_16x16x32_bf16 v[4:7], v[160:163], v[212:215], v[4:7]
	v_mfma_f32_16x16x32_bf16 v[0:3], v[176:179], v[212:215], v[0:3]
	v_mfma_f32_16x16x32_bf16 v[52:55], v[172:175], v[188:191], v[52:55]
	v_mfma_f32_16x16x32_bf16 v[44:47], v[180:183], v[188:191], v[44:47]
	v_mfma_f32_16x16x32_bf16 v[36:39], v[172:175], v[196:199], v[36:39]
	v_mfma_f32_16x16x32_bf16 v[28:31], v[180:183], v[196:199], v[28:31]
	v_mfma_f32_16x16x32_bf16 v[20:23], v[172:175], v[208:211], v[20:23]
	v_mfma_f32_16x16x32_bf16 v[12:15], v[180:183], v[208:211], v[12:15]
	v_mfma_f32_16x16x32_bf16 v[4:7], v[172:175], v[216:219], v[4:7]
	v_mfma_f32_16x16x32_bf16 v[0:3], v[180:183], v[216:219], v[0:3]
	s_barrier
	s_setprio 0
	s_add_i32 s92, s92, 2
	s_add_u32 s22, s22, 0x100
	s_addc_u32 s23, s23, 0
	s_add_u32 s90, s90, 0x100
	s_addc_u32 s91, s91, 0
	s_cmp_gt_u32 s92, 13
	s_cbranch_scc0 .LBB0_199
	s_and_b64 vcc, exec, s[10:11]
	s_cbranch_vccz .LBB0_202
	s_barrier

.LBB0_522:
	ds_read_b128 v[128:131], v203
	ds_read_b128 v[132:135], v203 offset:1024
	ds_read_b128 v[136:139], v203 offset:2048
	ds_read_b128 v[140:143], v203 offset:3072
	ds_read_b128 v[144:147], v204
	ds_read_b128 v[148:151], v204 offset:1024
	ds_read_b128 v[152:155], v204 offset:2048
	ds_read_b128 v[156:159], v204 offset:3072
	s_add_u32 s28, s26, 0x100
	s_addc_u32 s29, s27, 0
	s_cmp_eq_u32 s94, 12
	s_cselect_b32 s35, s3, s29
	s_cselect_b32 s34, s17, s28
	s_cselect_b32 s31, s15, s93
	s_cselect_b32 s30, s23, s92
	v_lshl_add_u64 v[214:215], s[26:27], 0, v[180:181]
	s_add_i32 m0, s25, 0xc000
	ds_read_b128 v[160:163], v205
	ds_read_b128 v[164:167], v205 offset:1024
	ds_read_b128 v[168:171], v205 offset:2048
	ds_read_b128 v[172:175], v205 offset:3072
	ds_read_b128 v[188:191], v205 offset:4096
	ds_read_b128 v[192:195], v205 offset:5120
	ds_read_b128 v[196:199], v205 offset:6144
	ds_read_b128 v[210:213], v205 offset:7168
	global_load_lds_dwordx4 v[214:215], off
	v_lshl_add_u64 v[214:215], s[26:27], 0, v[182:183]
	s_add_i32 m0, s25, 0xe000
	s_nop 0
	global_load_lds_dwordx4 v[214:215], off
	s_waitcnt vmcnt(8)
	s_waitcnt lgkmcnt(0)
	s_setprio 1
	s_barrier
	v_mfma_f32_16x16x32_bf16 v[124:127], v[128:131], v[160:163], v[124:127]
	v_mfma_f32_16x16x32_bf16 v[120:123], v[136:139], v[160:163], v[120:123]
	v_mfma_f32_16x16x32_bf16 v[108:111], v[128:131], v[168:171], v[108:111]
	v_mfma_f32_16x16x32_bf16 v[104:107], v[136:139], v[168:171], v[104:107]
	v_mfma_f32_16x16x32_bf16 v[92:95], v[128:131], v[188:191], v[92:95]
	v_mfma_f32_16x16x32_bf16 v[88:91], v[136:139], v[188:191], v[88:91]
	v_mfma_f32_16x16x32_bf16 v[76:79], v[128:131], v[196:199], v[76:79]
	v_mfma_f32_16x16x32_bf16 v[72:75], v[136:139], v[196:199], v[72:75]
	v_mfma_f32_16x16x32_bf16 v[124:127], v[132:135], v[164:167], v[124:127]
	v_mfma_f32_16x16x32_bf16 v[120:123], v[140:143], v[164:167], v[120:123]
	v_mfma_f32_16x16x32_bf16 v[108:111], v[132:135], v[172:175], v[108:111]
	v_mfma_f32_16x16x32_bf16 v[104:107], v[140:143], v[172:175], v[104:107]
	v_mfma_f32_16x16x32_bf16 v[92:95], v[132:135], v[192:195], v[92:95]
	v_mfma_f32_16x16x32_bf16 v[88:91], v[140:143], v[192:195], v[88:91]
	v_mfma_f32_16x16x32_bf16 v[76:79], v[132:135], v[210:213], v[76:79]
	v_mfma_f32_16x16x32_bf16 v[72:75], v[140:143], v[210:213], v[72:75]
	s_setprio 0
	s_setprio 1
	v_mfma_f32_16x16x32_bf16 v[116:119], v[144:147], v[160:163], v[116:119]
	v_mfma_f32_16x16x32_bf16 v[112:115], v[152:155], v[160:163], v[112:115]
	v_mfma_f32_16x16x32_bf16 v[100:103], v[144:147], v[168:171], v[100:103]
	v_mfma_f32_16x16x32_bf16 v[96:99], v[152:155], v[168:171], v[96:99]
	v_mfma_f32_16x16x32_bf16 v[84:87], v[144:147], v[188:191], v[84:87]
	v_mfma_f32_16x16x32_bf16 v[80:83], v[152:155], v[188:191], v[80:83]
	v_mfma_f32_16x16x32_bf16 v[68:71], v[144:147], v[196:199], v[68:71]
	v_mfma_f32_16x16x32_bf16 v[64:67], v[152:155], v[196:199], v[64:67]
	v_mfma_f32_16x16x32_bf16 v[116:119], v[148:151], v[164:167], v[116:119]
	v_mfma_f32_16x16x32_bf16 v[112:115], v[156:159], v[164:167], v[112:115]
	v_mfma_f32_16x16x32_bf16 v[100:103], v[148:151], v[172:175], v[100:103]
	v_mfma_f32_16x16x32_bf16 v[96:99], v[156:159], v[172:175], v[96:99]
	v_mfma_f32_16x16x32_bf16 v[84:87], v[148:151], v[192:195], v[84:87]
	v_mfma_f32_16x16x32_bf16 v[80:83], v[156:159], v[192:195], v[80:83]
	v_mfma_f32_16x16x32_bf16 v[68:71], v[148:151], v[210:213], v[68:71]
	v_mfma_f32_16x16x32_bf16 v[64:67], v[156:159], v[210:213], v[64:67]
	s_barrier
	s_setprio 0
	s_add_i32 s26, s90, s51
	v_lshl_add_u64 v[214:215], s[30:31], 0, v[176:177]
	s_mov_b32 m0, s26
	ds_read_b128 v[160:163], v205 offset:16384
	ds_read_b128 v[164:167], v205 offset:17408
	ds_read_b128 v[168:171], v205 offset:18432
	ds_read_b128 v[172:175], v205 offset:19456
	ds_read_b128 v[188:191], v205 offset:20480
	ds_read_b128 v[192:195], v205 offset:21504
	ds_read_b128 v[196:199], v205 offset:22528
	ds_read_b128 v[210:213], v205 offset:23552
	global_load_lds_dwordx4 v[214:215], off
	s_add_i32 m0, s26, 0x2000
	s_add_u32 s26, s30, 0x40000
	v_lshl_add_u64 v[216:217], s[30:31], 0, v[178:179]
	s_addc_u32 s27, s31, 0
	s_add_i32 s95, s91, s51
	global_load_lds_dwordx4 v[216:217], off
	v_lshl_add_u64 v[218:219], s[26:27], 0, v[176:177]
	s_mov_b32 m0, s95
	v_lshl_add_u64 v[220:221], s[34:35], 0, v[178:179]
	global_load_lds_dwordx4 v[218:219], off
	v_lshl_add_u64 v[218:219], s[26:27], 0, v[178:179]
	s_add_i32 m0, s95, 0x2000
	s_nop 0
	global_load_lds_dwordx4 v[218:219], off
	v_lshl_add_u64 v[218:219], s[34:35], 0, v[176:177]
	s_mov_b32 m0, s25
	s_nop 0
	global_load_lds_dwordx4 v[218:219], off
	s_mov_b32 m0, s76
	s_nop 0
	global_load_lds_dwordx4 v[220:221], off
	s_waitcnt vmcnt(8)
	s_waitcnt lgkmcnt(0)
	s_setprio 1
	s_barrier
	v_mfma_f32_16x16x32_bf16 v[60:63], v[128:131], v[160:163], v[60:63]
	v_mfma_f32_16x16x32_bf16 v[56:59], v[136:139], v[160:163], v[56:59]
	v_mfma_f32_16x16x32_bf16 v[44:47], v[128:131], v[168:171], v[44:47]
	v_mfma_f32_16x16x32_bf16 v[40:43], v[136:139], v[168:171], v[40:43]
	v_mfma_f32_16x16x32_bf16 v[28:31], v[128:131], v[188:191], v[28:31]
	v_mfma_f32_16x16x32_bf16 v[24:27], v[136:139], v[188:191], v[24:27]
	v_mfma_f32_16x16x32_bf16 v[12:15], v[128:131], v[196:199], v[12:15]
	v_mfma_f32_16x16x32_bf16 v[8:11], v[136:139], v[196:199], v[8:11]
	v_mfma_f32_16x16x32_bf16 v[60:63], v[132:135], v[164:167], v[60:63]
	v_mfma_f32_16x16x32_bf16 v[56:59], v[140:143], v[164:167], v[56:59]
	v_mfma_f32_16x16x32_bf16 v[44:47], v[132:135], v[172:175], v[44:47]
	v_mfma_f32_16x16x32_bf16 v[40:43], v[140:143], v[172:175], v[40:43]
	v_mfma_f32_16x16x32_bf16 v[28:31], v[132:135], v[192:195], v[28:31]
	v_mfma_f32_16x16x32_bf16 v[24:27], v[140:143], v[192:195], v[24:27]
	v_mfma_f32_16x16x32_bf16 v[12:15], v[132:135], v[210:213], v[12:15]
	v_mfma_f32_16x16x32_bf16 v[8:11], v[140:143], v[210:213], v[8:11]
	s_setprio 0
	s_setprio 1
	v_mfma_f32_16x16x32_bf16 v[52:55], v[144:147], v[160:163], v[52:55]
	v_mfma_f32_16x16x32_bf16 v[48:51], v[152:155], v[160:163], v[48:51]
	v_mfma_f32_16x16x32_bf16 v[36:39], v[144:147], v[168:171], v[36:39]
	v_mfma_f32_16x16x32_bf16 v[32:35], v[152:155], v[168:171], v[32:35]
	v_mfma_f32_16x16x32_bf16 v[20:23], v[144:147], v[188:191], v[20:23]
	v_mfma_f32_16x16x32_bf16 v[16:19], v[152:155], v[188:191], v[16:19]
	v_mfma_f32_16x16x32_bf16 v[4:7], v[144:147], v[196:199], v[4:7]
	v_mfma_f32_16x16x32_bf16 v[0:3], v[152:155], v[196:199], v[0:3]
	v_mfma_f32_16x16x32_bf16 v[52:55], v[148:151], v[164:167], v[52:55]
	v_mfma_f32_16x16x32_bf16 v[48:51], v[156:159], v[164:167], v[48:51]
	v_mfma_f32_16x16x32_bf16 v[36:39], v[148:151], v[172:175], v[36:39]
	v_mfma_f32_16x16x32_bf16 v[32:35], v[156:159], v[172:175], v[32:35]
	v_mfma_f32_16x16x32_bf16 v[20:23], v[148:151], v[192:195], v[20:23]
	v_mfma_f32_16x16x32_bf16 v[16:19], v[156:159], v[192:195], v[16:19]
	v_mfma_f32_16x16x32_bf16 v[4:7], v[148:151], v[210:213], v[4:7]
	v_mfma_f32_16x16x32_bf16 v[0:3], v[156:159], v[210:213], v[0:3]
	s_barrier
	s_setprio 0
	s_add_i32 s95, 0, 0x18000
	s_add_i32 s96, 0, 0x1c000
	v_add_u32_e32 v140, s95, v201
	v_add_u32_e32 v156, s96, v201
	ds_read_b128 v[128:131], v140
	ds_read_b128 v[132:135], v140 offset:1024
	ds_read_b128 v[136:139], v140 offset:2048
	ds_read_b128 v[140:143], v140 offset:3072
	ds_read_b128 v[144:147], v156
	ds_read_b128 v[148:151], v156 offset:1024
	ds_read_b128 v[152:155], v156 offset:2048
	ds_read_b128 v[156:159], v156 offset:3072
	s_add_u32 s26, s34, 0x40000
	s_addc_u32 s27, s35, 0
	s_mov_b32 m0, s77
	v_lshl_add_u64 v[222:223], s[26:27], 0, v[176:177]
	ds_read_b128 v[160:163], v205 offset:32768
	ds_read_b128 v[164:167], v205 offset:33792
	ds_read_b128 v[168:171], v205 offset:34816
	ds_read_b128 v[172:175], v205 offset:35840
	ds_read_b128 v[188:191], v205 offset:36864
	ds_read_b128 v[192:195], v205 offset:37888
	ds_read_b128 v[196:199], v205 offset:38912
	ds_read_b128 v[210:213], v205 offset:39936
	global_load_lds_dwordx4 v[222:223], off
	v_lshl_add_u64 v[222:223], s[26:27], 0, v[178:179]
	s_mov_b32 m0, s78
	s_nop 0
	global_load_lds_dwordx4 v[222:223], off
	s_waitcnt vmcnt(8)
	s_waitcnt lgkmcnt(0)
	s_setprio 1
	s_barrier
	v_mfma_f32_16x16x32_bf16 v[124:127], v[128:131], v[160:163], v[124:127]
	v_mfma_f32_16x16x32_bf16 v[120:123], v[136:139], v[160:163], v[120:123]
	v_mfma_f32_16x16x32_bf16 v[108:111], v[128:131], v[168:171], v[108:111]
	v_mfma_f32_16x16x32_bf16 v[104:107], v[136:139], v[168:171], v[104:107]
	v_mfma_f32_16x16x32_bf16 v[92:95], v[128:131], v[188:191], v[92:95]
	v_mfma_f32_16x16x32_bf16 v[88:91], v[136:139], v[188:191], v[88:91]
	v_mfma_f32_16x16x32_bf16 v[76:79], v[128:131], v[196:199], v[76:79]
	v_mfma_f32_16x16x32_bf16 v[72:75], v[136:139], v[196:199], v[72:75]
	v_mfma_f32_16x16x32_bf16 v[124:127], v[132:135], v[164:167], v[124:127]
	v_mfma_f32_16x16x32_bf16 v[120:123], v[140:143], v[164:167], v[120:123]
	v_mfma_f32_16x16x32_bf16 v[108:111], v[132:135], v[172:175], v[108:111]
	v_mfma_f32_16x16x32_bf16 v[104:107], v[140:143], v[172:175], v[104:107]
	v_mfma_f32_16x16x32_bf16 v[92:95], v[132:135], v[192:195], v[92:95]
	v_mfma_f32_16x16x32_bf16 v[88:91], v[140:143], v[192:195], v[88:91]
	v_mfma_f32_16x16x32_bf16 v[76:79], v[132:135], v[210:213], v[76:79]
	v_mfma_f32_16x16x32_bf16 v[72:75], v[140:143], v[210:213], v[72:75]
	s_setprio 0
	s_setprio 1
	v_mfma_f32_16x16x32_bf16 v[116:119], v[144:147], v[160:163], v[116:119]
	v_mfma_f32_16x16x32_bf16 v[112:115], v[152:155], v[160:163], v[112:115]
	v_mfma_f32_16x16x32_bf16 v[100:103], v[144:147], v[168:171], v[100:103]
	v_mfma_f32_16x16x32_bf16 v[96:99], v[152:155], v[168:171], v[96:99]
	v_mfma_f32_16x16x32_bf16 v[84:87], v[144:147], v[188:191], v[84:87]
	v_mfma_f32_16x16x32_bf16 v[80:83], v[152:155], v[188:191], v[80:83]
	v_mfma_f32_16x16x32_bf16 v[68:71], v[144:147], v[196:199], v[68:71]
	v_mfma_f32_16x16x32_bf16 v[64:67], v[152:155], v[196:199], v[64:67]
	v_mfma_f32_16x16x32_bf16 v[116:119], v[148:151], v[164:167], v[116:119]
	v_mfma_f32_16x16x32_bf16 v[112:115], v[156:159], v[164:167], v[112:115]
	v_mfma_f32_16x16x32_bf16 v[100:103], v[148:151], v[172:175], v[100:103]
	v_mfma_f32_16x16x32_bf16 v[96:99], v[156:159], v[172:175], v[96:99]
	v_mfma_f32_16x16x32_bf16 v[84:87], v[148:151], v[192:195], v[84:87]
	v_mfma_f32_16x16x32_bf16 v[80:83], v[156:159], v[192:195], v[80:83]
	v_mfma_f32_16x16x32_bf16 v[68:71], v[148:151], v[210:213], v[68:71]
	v_mfma_f32_16x16x32_bf16 v[64:67], v[156:159], v[210:213], v[64:67]
	s_barrier
	s_setprio 0
	s_add_i32 s26, s95, s51
	v_lshl_add_u64 v[214:215], v[214:215], 0, s[10:11]
	s_mov_b32 m0, s26
	ds_read_b128 v[160:163], v205 offset:49152
	ds_read_b128 v[164:167], v205 offset:50176
	ds_read_b128 v[168:171], v205 offset:51200
	ds_read_b128 v[172:175], v205 offset:52224
	ds_read_b128 v[188:191], v205 offset:53248
	ds_read_b128 v[192:195], v205 offset:54272
	ds_read_b128 v[196:199], v205 offset:55296
	ds_read_b128 v[210:213], v205 offset:56320
	global_load_lds_dwordx4 v[214:215], off
	s_add_i32 m0, s26, 0x2000
	s_add_u32 s26, s30, 0x40080
	v_lshl_add_u64 v[214:215], v[216:217], 0, s[10:11]
	s_addc_u32 s27, s31, 0
	s_add_i32 s30, s96, s51
	global_load_lds_dwordx4 v[214:215], off
	v_lshl_add_u64 v[214:215], s[26:27], 0, v[176:177]
	s_mov_b32 m0, s30
	s_nop 0
	global_load_lds_dwordx4 v[214:215], off
	v_lshl_add_u64 v[214:215], s[26:27], 0, v[178:179]
	s_add_i32 m0, s30, 0x2000
	s_nop 0
	global_load_lds_dwordx4 v[214:215], off
	v_lshl_add_u64 v[214:215], v[218:219], 0, s[10:11]
	s_mov_b32 m0, s86
	s_nop 0
	global_load_lds_dwordx4 v[214:215], off
	v_lshl_add_u64 v[214:215], v[220:221], 0, s[10:11]
	s_mov_b32 m0, s87
	s_nop 0
	global_load_lds_dwordx4 v[214:215], off
	s_waitcnt vmcnt(8)
	s_waitcnt lgkmcnt(0)
	s_setprio 1
	s_barrier
	v_mfma_f32_16x16x32_bf16 v[60:63], v[128:131], v[160:163], v[60:63]
	v_mfma_f32_16x16x32_bf16 v[56:59], v[136:139], v[160:163], v[56:59]
	v_mfma_f32_16x16x32_bf16 v[44:47], v[128:131], v[168:171], v[44:47]
	v_mfma_f32_16x16x32_bf16 v[40:43], v[136:139], v[168:171], v[40:43]
	v_mfma_f32_16x16x32_bf16 v[28:31], v[128:131], v[188:191], v[28:31]
	v_mfma_f32_16x16x32_bf16 v[24:27], v[136:139], v[188:191], v[24:27]
	v_mfma_f32_16x16x32_bf16 v[12:15], v[128:131], v[196:199], v[12:15]
	v_mfma_f32_16x16x32_bf16 v[8:11], v[136:139], v[196:199], v[8:11]
	v_mfma_f32_16x16x32_bf16 v[60:63], v[132:135], v[164:167], v[60:63]
	v_mfma_f32_16x16x32_bf16 v[56:59], v[140:143], v[164:167], v[56:59]
	v_mfma_f32_16x16x32_bf16 v[44:47], v[132:135], v[172:175], v[44:47]
	v_mfma_f32_16x16x32_bf16 v[40:43], v[140:143], v[172:175], v[40:43]
	v_mfma_f32_16x16x32_bf16 v[28:31], v[132:135], v[192:195], v[28:31]
	v_mfma_f32_16x16x32_bf16 v[24:27], v[140:143], v[192:195], v[24:27]
	v_mfma_f32_16x16x32_bf16 v[12:15], v[132:135], v[210:213], v[12:15]
	v_mfma_f32_16x16x32_bf16 v[8:11], v[140:143], v[210:213], v[8:11]
	s_setprio 0
	s_setprio 1
	v_mfma_f32_16x16x32_bf16 v[52:55], v[144:147], v[160:163], v[52:55]
	v_mfma_f32_16x16x32_bf16 v[48:51], v[152:155], v[160:163], v[48:51]
	v_mfma_f32_16x16x32_bf16 v[36:39], v[144:147], v[168:171], v[36:39]
	v_mfma_f32_16x16x32_bf16 v[32:35], v[152:155], v[168:171], v[32:35]
	v_mfma_f32_16x16x32_bf16 v[20:23], v[144:147], v[188:191], v[20:23]
	v_mfma_f32_16x16x32_bf16 v[16:19], v[152:155], v[188:191], v[16:19]
	v_mfma_f32_16x16x32_bf16 v[4:7], v[144:147], v[196:199], v[4:7]
	v_mfma_f32_16x16x32_bf16 v[0:3], v[152:155], v[196:199], v[0:3]
	v_mfma_f32_16x16x32_bf16 v[52:55], v[148:151], v[164:167], v[52:55]
	v_mfma_f32_16x16x32_bf16 v[48:51], v[156:159], v[164:167], v[48:51]
	v_mfma_f32_16x16x32_bf16 v[36:39], v[148:151], v[172:175], v[36:39]
	v_mfma_f32_16x16x32_bf16 v[32:35], v[156:159], v[172:175], v[32:35]
	v_mfma_f32_16x16x32_bf16 v[20:23], v[148:151], v[192:195], v[20:23]
	v_mfma_f32_16x16x32_bf16 v[16:19], v[156:159], v[192:195], v[16:19]
	v_mfma_f32_16x16x32_bf16 v[4:7], v[148:151], v[210:213], v[4:7]
	v_mfma_f32_16x16x32_bf16 v[0:3], v[156:159], v[210:213], v[0:3]
	s_barrier
	s_setprio 0
	s_add_i32 s94, s94, 2
	s_add_u32 s92, s92, 0x100
	s_addc_u32 s93, s93, 0
	s_cmp_gt_u32 s94, 13
	s_mov_b64 s[26:27], s[28:29]
	s_cbranch_scc0 .LBB0_522
	s_and_b64 vcc, exec, s[12:13]
	s_cbranch_vccz .LBB0_525
	s_barrier

.LBB0_694:
	ds_read_b128 v[144:147], v155
	ds_read_b128 v[148:151], v155 offset:1024
	ds_read_b128 v[160:163], v155 offset:2048
	ds_read_b128 v[164:167], v155 offset:3072
	ds_read_b128 v[168:171], v156
	ds_read_b128 v[172:175], v156 offset:1024
	ds_read_b128 v[176:179], v156 offset:2048
	ds_read_b128 v[180:183], v156 offset:3072
	s_add_u32 s26, s24, 0xfffc0080
	s_addc_u32 s27, s25, -1
	s_cmp_eq_u32 s91, 12
	s_cselect_b32 s29, s17, s27
	s_cselect_b32 s28, s87, s26
	s_cselect_b32 s27, s15, s90
	s_cselect_b32 s26, s88, s89
	v_lshl_add_u64 v[204:205], s[24:25], 0, v[136:137]
	s_add_i32 m0, s23, 0xc000
	ds_read_b128 v[184:187], v157
	ds_read_b128 v[188:191], v157 offset:1024
	ds_read_b128 v[192:195], v157 offset:2048
	ds_read_b128 v[196:199], v157 offset:3072
	ds_read_b128 v[200:203], v157 offset:4096
	ds_read_b128 v[208:211], v157 offset:5120
	ds_read_b128 v[212:215], v157 offset:6144
	ds_read_b128 v[216:219], v157 offset:7168
	global_load_lds_dwordx4 v[204:205], off
	v_lshl_add_u64 v[204:205], s[24:25], 0, v[138:139]
	s_add_i32 m0, s23, 0xe000
	s_nop 0
	global_load_lds_dwordx4 v[204:205], off
	s_waitcnt vmcnt(8)
	s_waitcnt lgkmcnt(0)
	s_setprio 1
	s_barrier
	v_mfma_f32_16x16x32_bf16 v[124:127], v[144:147], v[184:187], v[124:127]
	v_mfma_f32_16x16x32_bf16 v[120:123], v[160:163], v[184:187], v[120:123]
	v_mfma_f32_16x16x32_bf16 v[116:119], v[144:147], v[192:195], v[116:119]
	v_mfma_f32_16x16x32_bf16 v[104:107], v[160:163], v[192:195], v[104:107]
	v_mfma_f32_16x16x32_bf16 v[92:95], v[144:147], v[200:203], v[92:95]
	v_mfma_f32_16x16x32_bf16 v[88:91], v[160:163], v[200:203], v[88:91]
	v_mfma_f32_16x16x32_bf16 v[76:79], v[144:147], v[212:215], v[76:79]
	v_mfma_f32_16x16x32_bf16 v[72:75], v[160:163], v[212:215], v[72:75]
	v_mfma_f32_16x16x32_bf16 v[124:127], v[148:151], v[188:191], v[124:127]
	v_mfma_f32_16x16x32_bf16 v[120:123], v[164:167], v[188:191], v[120:123]
	v_mfma_f32_16x16x32_bf16 v[116:119], v[148:151], v[196:199], v[116:119]
	v_mfma_f32_16x16x32_bf16 v[104:107], v[164:167], v[196:199], v[104:107]
	v_mfma_f32_16x16x32_bf16 v[92:95], v[148:151], v[208:211], v[92:95]
	v_mfma_f32_16x16x32_bf16 v[88:91], v[164:167], v[208:211], v[88:91]
	v_mfma_f32_16x16x32_bf16 v[76:79], v[148:151], v[216:219], v[76:79]
	v_mfma_f32_16x16x32_bf16 v[72:75], v[164:167], v[216:219], v[72:75]
	s_setprio 0
	s_setprio 1
	v_mfma_f32_16x16x32_bf16 v[112:115], v[168:171], v[184:187], v[112:115]
	v_mfma_f32_16x16x32_bf16 v[108:111], v[176:179], v[184:187], v[108:111]
	v_mfma_f32_16x16x32_bf16 v[100:103], v[168:171], v[192:195], v[100:103]
	v_mfma_f32_16x16x32_bf16 v[96:99], v[176:179], v[192:195], v[96:99]
	v_mfma_f32_16x16x32_bf16 v[84:87], v[168:171], v[200:203], v[84:87]
	v_mfma_f32_16x16x32_bf16 v[80:83], v[176:179], v[200:203], v[80:83]
	v_mfma_f32_16x16x32_bf16 v[68:71], v[168:171], v[212:215], v[68:71]
	v_mfma_f32_16x16x32_bf16 v[64:67], v[176:179], v[212:215], v[64:67]
	v_mfma_f32_16x16x32_bf16 v[112:115], v[172:175], v[188:191], v[112:115]
	v_mfma_f32_16x16x32_bf16 v[108:111], v[180:183], v[188:191], v[108:111]
	v_mfma_f32_16x16x32_bf16 v[100:103], v[172:175], v[196:199], v[100:103]
	v_mfma_f32_16x16x32_bf16 v[96:99], v[180:183], v[196:199], v[96:99]
	v_mfma_f32_16x16x32_bf16 v[84:87], v[172:175], v[208:211], v[84:87]
	v_mfma_f32_16x16x32_bf16 v[80:83], v[180:183], v[208:211], v[80:83]
	v_mfma_f32_16x16x32_bf16 v[68:71], v[172:175], v[216:219], v[68:71]
	v_mfma_f32_16x16x32_bf16 v[64:67], v[180:183], v[216:219], v[64:67]
	s_barrier
	s_setprio 0
	s_add_i32 s92, s78, s37
	v_lshl_add_u64 v[204:205], s[26:27], 0, v[130:131]
	s_mov_b32 m0, s92
	ds_read_b128 v[184:187], v157 offset:16384
	ds_read_b128 v[188:191], v157 offset:17408
	ds_read_b128 v[192:195], v157 offset:18432
	ds_read_b128 v[196:199], v157 offset:19456
	ds_read_b128 v[200:203], v157 offset:20480
	ds_read_b128 v[208:211], v157 offset:21504
	ds_read_b128 v[212:215], v157 offset:22528
	ds_read_b128 v[216:219], v157 offset:23552
	global_load_lds_dwordx4 v[204:205], off
	s_add_i32 m0, s92, 0x2000
	s_add_u32 s92, s26, 0x40000
	v_lshl_add_u64 v[220:221], s[26:27], 0, v[134:135]
	s_addc_u32 s93, s27, 0
	s_add_i32 s94, s79, s37
	global_load_lds_dwordx4 v[220:221], off
	v_lshl_add_u64 v[222:223], s[92:93], 0, v[130:131]
	s_mov_b32 m0, s94
	v_lshl_add_u64 v[224:225], s[28:29], 0, v[132:133]
	global_load_lds_dwordx4 v[222:223], off
	v_lshl_add_u64 v[222:223], s[92:93], 0, v[134:135]
	s_add_i32 m0, s94, 0x2000
	s_nop 0
	global_load_lds_dwordx4 v[222:223], off
	v_lshl_add_u64 v[222:223], s[28:29], 0, v[128:129]
	s_mov_b32 m0, s23
	s_nop 0
	global_load_lds_dwordx4 v[222:223], off
	s_mov_b32 m0, s39
	s_nop 0
	global_load_lds_dwordx4 v[224:225], off
	s_waitcnt vmcnt(8)
	s_waitcnt lgkmcnt(0)
	s_setprio 1
	s_barrier
	v_mfma_f32_16x16x32_bf16 v[60:63], v[144:147], v[184:187], v[60:63]
	v_mfma_f32_16x16x32_bf16 v[56:59], v[160:163], v[184:187], v[56:59]
	v_mfma_f32_16x16x32_bf16 v[44:47], v[144:147], v[192:195], v[44:47]
	v_mfma_f32_16x16x32_bf16 v[40:43], v[160:163], v[192:195], v[40:43]
	v_mfma_f32_16x16x32_bf16 v[28:31], v[144:147], v[200:203], v[28:31]
	v_mfma_f32_16x16x32_bf16 v[24:27], v[160:163], v[200:203], v[24:27]
	v_mfma_f32_16x16x32_bf16 v[12:15], v[144:147], v[212:215], v[12:15]
	v_mfma_f32_16x16x32_bf16 v[8:11], v[160:163], v[212:215], v[8:11]
	v_mfma_f32_16x16x32_bf16 v[60:63], v[148:151], v[188:191], v[60:63]
	v_mfma_f32_16x16x32_bf16 v[56:59], v[164:167], v[188:191], v[56:59]
	v_mfma_f32_16x16x32_bf16 v[44:47], v[148:151], v[196:199], v[44:47]
	v_mfma_f32_16x16x32_bf16 v[40:43], v[164:167], v[196:199], v[40:43]
	v_mfma_f32_16x16x32_bf16 v[28:31], v[148:151], v[208:211], v[28:31]
	v_mfma_f32_16x16x32_bf16 v[24:27], v[164:167], v[208:211], v[24:27]
	v_mfma_f32_16x16x32_bf16 v[12:15], v[148:151], v[216:219], v[12:15]
	v_mfma_f32_16x16x32_bf16 v[8:11], v[164:167], v[216:219], v[8:11]
	s_setprio 0
	s_setprio 1
	v_mfma_f32_16x16x32_bf16 v[52:55], v[168:171], v[184:187], v[52:55]
	v_mfma_f32_16x16x32_bf16 v[48:51], v[176:179], v[184:187], v[48:51]
	v_mfma_f32_16x16x32_bf16 v[36:39], v[168:171], v[192:195], v[36:39]
	v_mfma_f32_16x16x32_bf16 v[32:35], v[176:179], v[192:195], v[32:35]
	v_mfma_f32_16x16x32_bf16 v[20:23], v[168:171], v[200:203], v[20:23]
	v_mfma_f32_16x16x32_bf16 v[16:19], v[176:179], v[200:203], v[16:19]
	v_mfma_f32_16x16x32_bf16 v[4:7], v[168:171], v[212:215], v[4:7]
	v_mfma_f32_16x16x32_bf16 v[0:3], v[176:179], v[212:215], v[0:3]
	v_mfma_f32_16x16x32_bf16 v[52:55], v[172:175], v[188:191], v[52:55]
	v_mfma_f32_16x16x32_bf16 v[48:51], v[180:183], v[188:191], v[48:51]
	v_mfma_f32_16x16x32_bf16 v[36:39], v[172:175], v[196:199], v[36:39]
	v_mfma_f32_16x16x32_bf16 v[32:35], v[180:183], v[196:199], v[32:35]
	v_mfma_f32_16x16x32_bf16 v[20:23], v[172:175], v[208:211], v[20:23]
	v_mfma_f32_16x16x32_bf16 v[16:19], v[180:183], v[208:211], v[16:19]
	v_mfma_f32_16x16x32_bf16 v[4:7], v[172:175], v[216:219], v[4:7]
	v_mfma_f32_16x16x32_bf16 v[0:3], v[180:183], v[216:219], v[0:3]
	s_barrier
	s_setprio 0
	s_add_i32 s92, 0, 0x18000
	v_add_u32_e32 v159, s92, v153
	s_add_i32 s93, 0, 0x1c000
	ds_read_b128 v[144:147], v159
	ds_read_b128 v[148:151], v159 offset:1024
	ds_read_b128 v[160:163], v159 offset:2048
	ds_read_b128 v[164:167], v159 offset:3072
	v_add_u32_e32 v159, s93, v153
	ds_read_b128 v[168:171], v159
	ds_read_b128 v[172:175], v159 offset:1024
	ds_read_b128 v[176:179], v159 offset:2048
	ds_read_b128 v[180:183], v159 offset:3072
	s_add_u32 s28, s28, 0x40000
	s_addc_u32 s29, s29, 0
	s_mov_b32 m0, s40
	v_lshl_add_u64 v[226:227], s[28:29], 0, v[128:129]
	ds_read_b128 v[184:187], v157 offset:32768
	ds_read_b128 v[188:191], v157 offset:33792
	ds_read_b128 v[192:195], v157 offset:34816
	ds_read_b128 v[196:199], v157 offset:35840
	ds_read_b128 v[200:203], v157 offset:36864
	ds_read_b128 v[208:211], v157 offset:37888
	ds_read_b128 v[212:215], v157 offset:38912
	ds_read_b128 v[216:219], v157 offset:39936
	global_load_lds_dwordx4 v[226:227], off
	v_lshl_add_u64 v[226:227], s[28:29], 0, v[132:133]
	s_mov_b32 m0, s41
	s_nop 0
	global_load_lds_dwordx4 v[226:227], off
	s_waitcnt vmcnt(8)
	s_waitcnt lgkmcnt(0)
	s_setprio 1
	s_barrier
	v_mfma_f32_16x16x32_bf16 v[124:127], v[144:147], v[184:187], v[124:127]
	v_mfma_f32_16x16x32_bf16 v[120:123], v[160:163], v[184:187], v[120:123]
	v_mfma_f32_16x16x32_bf16 v[116:119], v[144:147], v[192:195], v[116:119]
	v_mfma_f32_16x16x32_bf16 v[104:107], v[160:163], v[192:195], v[104:107]
	v_mfma_f32_16x16x32_bf16 v[92:95], v[144:147], v[200:203], v[92:95]
	v_mfma_f32_16x16x32_bf16 v[88:91], v[160:163], v[200:203], v[88:91]
	v_mfma_f32_16x16x32_bf16 v[76:79], v[144:147], v[212:215], v[76:79]
	v_mfma_f32_16x16x32_bf16 v[72:75], v[160:163], v[212:215], v[72:75]
	v_mfma_f32_16x16x32_bf16 v[124:127], v[148:151], v[188:191], v[124:127]
	v_mfma_f32_16x16x32_bf16 v[120:123], v[164:167], v[188:191], v[120:123]
	v_mfma_f32_16x16x32_bf16 v[116:119], v[148:151], v[196:199], v[116:119]
	v_mfma_f32_16x16x32_bf16 v[104:107], v[164:167], v[196:199], v[104:107]
	v_mfma_f32_16x16x32_bf16 v[92:95], v[148:151], v[208:211], v[92:95]
	v_mfma_f32_16x16x32_bf16 v[88:91], v[164:167], v[208:211], v[88:91]
	v_mfma_f32_16x16x32_bf16 v[76:79], v[148:151], v[216:219], v[76:79]
	v_mfma_f32_16x16x32_bf16 v[72:75], v[164:167], v[216:219], v[72:75]
	s_setprio 0
	s_setprio 1
	v_mfma_f32_16x16x32_bf16 v[112:115], v[168:171], v[184:187], v[112:115]
	v_mfma_f32_16x16x32_bf16 v[108:111], v[176:179], v[184:187], v[108:111]
	v_mfma_f32_16x16x32_bf16 v[100:103], v[168:171], v[192:195], v[100:103]
	v_mfma_f32_16x16x32_bf16 v[96:99], v[176:179], v[192:195], v[96:99]
	v_mfma_f32_16x16x32_bf16 v[84:87], v[168:171], v[200:203], v[84:87]
	v_mfma_f32_16x16x32_bf16 v[80:83], v[176:179], v[200:203], v[80:83]
	v_mfma_f32_16x16x32_bf16 v[68:71], v[168:171], v[212:215], v[68:71]
	v_mfma_f32_16x16x32_bf16 v[64:67], v[176:179], v[212:215], v[64:67]
	v_mfma_f32_16x16x32_bf16 v[112:115], v[172:175], v[188:191], v[112:115]
	v_mfma_f32_16x16x32_bf16 v[108:111], v[180:183], v[188:191], v[108:111]
	v_mfma_f32_16x16x32_bf16 v[100:103], v[172:175], v[196:199], v[100:103]
	v_mfma_f32_16x16x32_bf16 v[96:99], v[180:183], v[196:199], v[96:99]
	v_mfma_f32_16x16x32_bf16 v[84:87], v[172:175], v[208:211], v[84:87]
	v_mfma_f32_16x16x32_bf16 v[80:83], v[180:183], v[208:211], v[80:83]
	v_mfma_f32_16x16x32_bf16 v[68:71], v[172:175], v[216:219], v[68:71]
	v_mfma_f32_16x16x32_bf16 v[64:67], v[180:183], v[216:219], v[64:67]
	s_barrier
	s_setprio 0
	s_add_i32 s28, s92, s37
	v_lshl_add_u64 v[204:205], v[204:205], 0, s[8:9]
	s_mov_b32 m0, s28
	ds_read_b128 v[184:187], v157 offset:49152
	ds_read_b128 v[188:191], v157 offset:50176
	ds_read_b128 v[192:195], v157 offset:51200
	ds_read_b128 v[196:199], v157 offset:52224
	ds_read_b128 v[200:203], v157 offset:53248
	ds_read_b128 v[208:211], v157 offset:54272
	ds_read_b128 v[212:215], v157 offset:55296
	ds_read_b128 v[216:219], v157 offset:56320
	global_load_lds_dwordx4 v[204:205], off
	s_add_i32 m0, s28, 0x2000
	s_add_u32 s26, s26, 0x40080
	v_lshl_add_u64 v[204:205], v[220:221], 0, s[8:9]
	s_addc_u32 s27, s27, 0
	s_add_i32 s28, s93, s37
	global_load_lds_dwordx4 v[204:205], off
	v_lshl_add_u64 v[204:205], s[26:27], 0, v[130:131]
	s_mov_b32 m0, s28
	s_nop 0
	global_load_lds_dwordx4 v[204:205], off
	v_lshl_add_u64 v[204:205], s[26:27], 0, v[134:135]
	s_add_i32 m0, s28, 0x2000
	s_nop 0
	global_load_lds_dwordx4 v[204:205], off
	v_lshl_add_u64 v[204:205], v[222:223], 0, s[8:9]
	s_mov_b32 m0, s51
	s_nop 0
	global_load_lds_dwordx4 v[204:205], off
	v_lshl_add_u64 v[204:205], v[224:225], 0, s[8:9]
	s_mov_b32 m0, s76
	s_nop 0
	global_load_lds_dwordx4 v[204:205], off
	s_waitcnt vmcnt(8)
	s_waitcnt lgkmcnt(0)
	s_setprio 1
	s_barrier
	v_mfma_f32_16x16x32_bf16 v[60:63], v[144:147], v[184:187], v[60:63]
	v_mfma_f32_16x16x32_bf16 v[56:59], v[160:163], v[184:187], v[56:59]
	v_mfma_f32_16x16x32_bf16 v[44:47], v[144:147], v[192:195], v[44:47]
	v_mfma_f32_16x16x32_bf16 v[40:43], v[160:163], v[192:195], v[40:43]
	v_mfma_f32_16x16x32_bf16 v[28:31], v[144:147], v[200:203], v[28:31]
	v_mfma_f32_16x16x32_bf16 v[24:27], v[160:163], v[200:203], v[24:27]
	v_mfma_f32_16x16x32_bf16 v[12:15], v[144:147], v[212:215], v[12:15]
	v_mfma_f32_16x16x32_bf16 v[8:11], v[160:163], v[212:215], v[8:11]
	v_mfma_f32_16x16x32_bf16 v[60:63], v[148:151], v[188:191], v[60:63]
	v_mfma_f32_16x16x32_bf16 v[56:59], v[164:167], v[188:191], v[56:59]
	v_mfma_f32_16x16x32_bf16 v[44:47], v[148:151], v[196:199], v[44:47]
	v_mfma_f32_16x16x32_bf16 v[40:43], v[164:167], v[196:199], v[40:43]
	v_mfma_f32_16x16x32_bf16 v[28:31], v[148:151], v[208:211], v[28:31]
	v_mfma_f32_16x16x32_bf16 v[24:27], v[164:167], v[208:211], v[24:27]
	v_mfma_f32_16x16x32_bf16 v[12:15], v[148:151], v[216:219], v[12:15]
	v_mfma_f32_16x16x32_bf16 v[8:11], v[164:167], v[216:219], v[8:11]
	s_setprio 0
	s_setprio 1
	v_mfma_f32_16x16x32_bf16 v[52:55], v[168:171], v[184:187], v[52:55]
	v_mfma_f32_16x16x32_bf16 v[48:51], v[176:179], v[184:187], v[48:51]
	v_mfma_f32_16x16x32_bf16 v[36:39], v[168:171], v[192:195], v[36:39]
	v_mfma_f32_16x16x32_bf16 v[32:35], v[176:179], v[192:195], v[32:35]
	v_mfma_f32_16x16x32_bf16 v[20:23], v[168:171], v[200:203], v[20:23]
	v_mfma_f32_16x16x32_bf16 v[16:19], v[176:179], v[200:203], v[16:19]
	v_mfma_f32_16x16x32_bf16 v[4:7], v[168:171], v[212:215], v[4:7]
	v_mfma_f32_16x16x32_bf16 v[0:3], v[176:179], v[212:215], v[0:3]
	v_mfma_f32_16x16x32_bf16 v[52:55], v[172:175], v[188:191], v[52:55]
	v_mfma_f32_16x16x32_bf16 v[48:51], v[180:183], v[188:191], v[48:51]
	v_mfma_f32_16x16x32_bf16 v[36:39], v[172:175], v[196:199], v[36:39]
	v_mfma_f32_16x16x32_bf16 v[32:35], v[180:183], v[196:199], v[32:35]
	v_mfma_f32_16x16x32_bf16 v[20:23], v[172:175], v[208:211], v[20:23]
	v_mfma_f32_16x16x32_bf16 v[16:19], v[180:183], v[208:211], v[16:19]
	v_mfma_f32_16x16x32_bf16 v[4:7], v[172:175], v[216:219], v[4:7]
	v_mfma_f32_16x16x32_bf16 v[0:3], v[180:183], v[216:219], v[0:3]
	s_barrier
	s_setprio 0
	s_add_i32 s91, s91, 2
	s_add_u32 s24, s24, 0x100
	s_addc_u32 s25, s25, 0
	s_add_u32 s89, s89, 0x100
	s_addc_u32 s90, s90, 0
	s_cmp_gt_u32 s91, 13
	s_cbranch_scc0 .LBB0_694
	s_and_b64 vcc, exec, s[10:11]
	s_cbranch_vccz .LBB0_697
	s_barrier

.LBB0_852:
	ds_read_b128 v[128:131], v211
	ds_read_b128 v[132:135], v211 offset:1024
	ds_read_b128 v[136:139], v211 offset:2048
	ds_read_b128 v[140:143], v211 offset:3072
	ds_read_b128 v[144:147], v212
	ds_read_b128 v[148:151], v212 offset:1024
	ds_read_b128 v[152:155], v212 offset:2048
	ds_read_b128 v[156:159], v212 offset:3072
	s_add_u32 s28, s26, 0x100
	s_addc_u32 s29, s27, 0
	s_cmp_eq_u32 s92, 60
	s_cselect_b32 s35, s3, s29
	s_cselect_b32 s34, s17, s28
	s_cselect_b32 s31, s15, s91
	s_cselect_b32 s30, s23, s90
	v_lshl_add_u64 v[204:205], s[26:27], 0, v[180:181]
	s_add_i32 m0, s25, 0xc000
	ds_read_b128 v[160:163], v213
	ds_read_b128 v[164:167], v213 offset:1024
	ds_read_b128 v[168:171], v213 offset:2048
	ds_read_b128 v[172:175], v213 offset:3072
	ds_read_b128 v[188:191], v213 offset:4096
	ds_read_b128 v[192:195], v213 offset:5120
	ds_read_b128 v[196:199], v213 offset:6144
	ds_read_b128 v[200:203], v213 offset:7168
	global_load_lds_dwordx4 v[204:205], off
	v_lshl_add_u64 v[204:205], s[26:27], 0, v[182:183]
	s_add_i32 m0, s25, 0xe000
	s_nop 0
	global_load_lds_dwordx4 v[204:205], off
	s_waitcnt vmcnt(8)
	s_waitcnt lgkmcnt(0)
	s_setprio 1
	s_barrier
	v_mfma_f32_16x16x32_bf16 v[124:127], v[128:131], v[160:163], v[124:127]
	v_mfma_f32_16x16x32_bf16 v[120:123], v[136:139], v[160:163], v[120:123]
	v_mfma_f32_16x16x32_bf16 v[108:111], v[128:131], v[168:171], v[108:111]
	v_mfma_f32_16x16x32_bf16 v[104:107], v[136:139], v[168:171], v[104:107]
	v_mfma_f32_16x16x32_bf16 v[92:95], v[128:131], v[188:191], v[92:95]
	v_mfma_f32_16x16x32_bf16 v[88:91], v[136:139], v[188:191], v[88:91]
	v_mfma_f32_16x16x32_bf16 v[76:79], v[128:131], v[196:199], v[76:79]
	v_mfma_f32_16x16x32_bf16 v[72:75], v[136:139], v[196:199], v[72:75]
	v_mfma_f32_16x16x32_bf16 v[124:127], v[132:135], v[164:167], v[124:127]
	v_mfma_f32_16x16x32_bf16 v[120:123], v[140:143], v[164:167], v[120:123]
	v_mfma_f32_16x16x32_bf16 v[108:111], v[132:135], v[172:175], v[108:111]
	v_mfma_f32_16x16x32_bf16 v[104:107], v[140:143], v[172:175], v[104:107]
	v_mfma_f32_16x16x32_bf16 v[92:95], v[132:135], v[192:195], v[92:95]
	v_mfma_f32_16x16x32_bf16 v[88:91], v[140:143], v[192:195], v[88:91]
	v_mfma_f32_16x16x32_bf16 v[76:79], v[132:135], v[200:203], v[76:79]
	v_mfma_f32_16x16x32_bf16 v[72:75], v[140:143], v[200:203], v[72:75]
	s_setprio 0
	s_setprio 1
	v_mfma_f32_16x16x32_bf16 v[116:119], v[144:147], v[160:163], v[116:119]
	v_mfma_f32_16x16x32_bf16 v[112:115], v[152:155], v[160:163], v[112:115]
	v_mfma_f32_16x16x32_bf16 v[100:103], v[144:147], v[168:171], v[100:103]
	v_mfma_f32_16x16x32_bf16 v[96:99], v[152:155], v[168:171], v[96:99]
	v_mfma_f32_16x16x32_bf16 v[84:87], v[144:147], v[188:191], v[84:87]
	v_mfma_f32_16x16x32_bf16 v[80:83], v[152:155], v[188:191], v[80:83]
	v_mfma_f32_16x16x32_bf16 v[68:71], v[144:147], v[196:199], v[68:71]
	v_mfma_f32_16x16x32_bf16 v[64:67], v[152:155], v[196:199], v[64:67]
	v_mfma_f32_16x16x32_bf16 v[116:119], v[148:151], v[164:167], v[116:119]
	v_mfma_f32_16x16x32_bf16 v[112:115], v[156:159], v[164:167], v[112:115]
	v_mfma_f32_16x16x32_bf16 v[100:103], v[148:151], v[172:175], v[100:103]
	v_mfma_f32_16x16x32_bf16 v[96:99], v[156:159], v[172:175], v[96:99]
	v_mfma_f32_16x16x32_bf16 v[84:87], v[148:151], v[192:195], v[84:87]
	v_mfma_f32_16x16x32_bf16 v[80:83], v[156:159], v[192:195], v[80:83]
	v_mfma_f32_16x16x32_bf16 v[68:71], v[148:151], v[200:203], v[68:71]
	v_mfma_f32_16x16x32_bf16 v[64:67], v[156:159], v[200:203], v[64:67]
	s_barrier
	s_setprio 0
	s_add_i32 s26, s88, s41
	v_lshl_add_u64 v[204:205], s[30:31], 0, v[176:177]
	s_mov_b32 m0, s26
	ds_read_b128 v[160:163], v213 offset:16384
	ds_read_b128 v[164:167], v213 offset:17408
	ds_read_b128 v[168:171], v213 offset:18432
	ds_read_b128 v[172:175], v213 offset:19456
	ds_read_b128 v[188:191], v213 offset:20480
	ds_read_b128 v[192:195], v213 offset:21504
	ds_read_b128 v[196:199], v213 offset:22528
	ds_read_b128 v[200:203], v213 offset:23552
	global_load_lds_dwordx4 v[204:205], off
	s_add_i32 m0, s26, 0x2000
	s_add_u32 s26, s30, 0x100000
	v_lshl_add_u64 v[216:217], s[30:31], 0, v[178:179]
	s_addc_u32 s27, s31, 0
	s_add_i32 s93, s89, s41
	global_load_lds_dwordx4 v[216:217], off
	v_lshl_add_u64 v[218:219], s[26:27], 0, v[176:177]
	s_mov_b32 m0, s93
	v_lshl_add_u64 v[220:221], s[34:35], 0, v[178:179]
	global_load_lds_dwordx4 v[218:219], off
	v_lshl_add_u64 v[218:219], s[26:27], 0, v[178:179]
	s_add_i32 m0, s93, 0x2000
	s_nop 0
	global_load_lds_dwordx4 v[218:219], off
	v_lshl_add_u64 v[218:219], s[34:35], 0, v[176:177]
	s_mov_b32 m0, s25
	s_nop 0
	global_load_lds_dwordx4 v[218:219], off
	s_mov_b32 m0, s50
	s_nop 0
	global_load_lds_dwordx4 v[220:221], off
	s_waitcnt vmcnt(8)
	s_waitcnt lgkmcnt(0)
	s_setprio 1
	s_barrier
	v_mfma_f32_16x16x32_bf16 v[60:63], v[128:131], v[160:163], v[60:63]
	v_mfma_f32_16x16x32_bf16 v[56:59], v[136:139], v[160:163], v[56:59]
	v_mfma_f32_16x16x32_bf16 v[44:47], v[128:131], v[168:171], v[44:47]
	v_mfma_f32_16x16x32_bf16 v[40:43], v[136:139], v[168:171], v[40:43]
	v_mfma_f32_16x16x32_bf16 v[28:31], v[128:131], v[188:191], v[28:31]
	v_mfma_f32_16x16x32_bf16 v[24:27], v[136:139], v[188:191], v[24:27]
	v_mfma_f32_16x16x32_bf16 v[12:15], v[128:131], v[196:199], v[12:15]
	v_mfma_f32_16x16x32_bf16 v[8:11], v[136:139], v[196:199], v[8:11]
	v_mfma_f32_16x16x32_bf16 v[60:63], v[132:135], v[164:167], v[60:63]
	v_mfma_f32_16x16x32_bf16 v[56:59], v[140:143], v[164:167], v[56:59]
	v_mfma_f32_16x16x32_bf16 v[44:47], v[132:135], v[172:175], v[44:47]
	v_mfma_f32_16x16x32_bf16 v[40:43], v[140:143], v[172:175], v[40:43]
	v_mfma_f32_16x16x32_bf16 v[28:31], v[132:135], v[192:195], v[28:31]
	v_mfma_f32_16x16x32_bf16 v[24:27], v[140:143], v[192:195], v[24:27]
	v_mfma_f32_16x16x32_bf16 v[12:15], v[132:135], v[200:203], v[12:15]
	v_mfma_f32_16x16x32_bf16 v[8:11], v[140:143], v[200:203], v[8:11]
	s_setprio 0
	s_setprio 1
	v_mfma_f32_16x16x32_bf16 v[52:55], v[144:147], v[160:163], v[52:55]
	v_mfma_f32_16x16x32_bf16 v[48:51], v[152:155], v[160:163], v[48:51]
	v_mfma_f32_16x16x32_bf16 v[36:39], v[144:147], v[168:171], v[36:39]
	v_mfma_f32_16x16x32_bf16 v[32:35], v[152:155], v[168:171], v[32:35]
	v_mfma_f32_16x16x32_bf16 v[20:23], v[144:147], v[188:191], v[20:23]
	v_mfma_f32_16x16x32_bf16 v[16:19], v[152:155], v[188:191], v[16:19]
	v_mfma_f32_16x16x32_bf16 v[4:7], v[144:147], v[196:199], v[4:7]
	v_mfma_f32_16x16x32_bf16 v[0:3], v[152:155], v[196:199], v[0:3]
	v_mfma_f32_16x16x32_bf16 v[52:55], v[148:151], v[164:167], v[52:55]
	v_mfma_f32_16x16x32_bf16 v[48:51], v[156:159], v[164:167], v[48:51]
	v_mfma_f32_16x16x32_bf16 v[36:39], v[148:151], v[172:175], v[36:39]
	v_mfma_f32_16x16x32_bf16 v[32:35], v[156:159], v[172:175], v[32:35]
	v_mfma_f32_16x16x32_bf16 v[20:23], v[148:151], v[192:195], v[20:23]
	v_mfma_f32_16x16x32_bf16 v[16:19], v[156:159], v[192:195], v[16:19]
	v_mfma_f32_16x16x32_bf16 v[4:7], v[148:151], v[200:203], v[4:7]
	v_mfma_f32_16x16x32_bf16 v[0:3], v[156:159], v[200:203], v[0:3]
	s_barrier
	s_setprio 0
	s_add_i32 s93, 0, 0x18000
	s_add_i32 s94, 0, 0x1c000
	v_add_u32_e32 v140, s93, v209
	v_add_u32_e32 v156, s94, v209
	ds_read_b128 v[128:131], v140
	ds_read_b128 v[132:135], v140 offset:1024
	ds_read_b128 v[136:139], v140 offset:2048
	ds_read_b128 v[140:143], v140 offset:3072
	ds_read_b128 v[144:147], v156
	ds_read_b128 v[148:151], v156 offset:1024
	ds_read_b128 v[152:155], v156 offset:2048
	ds_read_b128 v[156:159], v156 offset:3072
	s_add_u32 s26, s34, 0x100000
	s_addc_u32 s27, s35, 0
	s_mov_b32 m0, s51
	v_lshl_add_u64 v[222:223], s[26:27], 0, v[176:177]
	ds_read_b128 v[160:163], v213 offset:32768
	ds_read_b128 v[164:167], v213 offset:33792
	ds_read_b128 v[168:171], v213 offset:34816
	ds_read_b128 v[172:175], v213 offset:35840
	ds_read_b128 v[188:191], v213 offset:36864
	ds_read_b128 v[192:195], v213 offset:37888
	ds_read_b128 v[196:199], v213 offset:38912
	ds_read_b128 v[200:203], v213 offset:39936
	global_load_lds_dwordx4 v[222:223], off
	v_lshl_add_u64 v[222:223], s[26:27], 0, v[178:179]
	s_mov_b32 m0, s76
	s_nop 0
	global_load_lds_dwordx4 v[222:223], off
	s_waitcnt vmcnt(8)
	s_waitcnt lgkmcnt(0)
	s_setprio 1
	s_barrier
	v_mfma_f32_16x16x32_bf16 v[124:127], v[128:131], v[160:163], v[124:127]
	v_mfma_f32_16x16x32_bf16 v[120:123], v[136:139], v[160:163], v[120:123]
	v_mfma_f32_16x16x32_bf16 v[108:111], v[128:131], v[168:171], v[108:111]
	v_mfma_f32_16x16x32_bf16 v[104:107], v[136:139], v[168:171], v[104:107]
	v_mfma_f32_16x16x32_bf16 v[92:95], v[128:131], v[188:191], v[92:95]
	v_mfma_f32_16x16x32_bf16 v[88:91], v[136:139], v[188:191], v[88:91]
	v_mfma_f32_16x16x32_bf16 v[76:79], v[128:131], v[196:199], v[76:79]
	v_mfma_f32_16x16x32_bf16 v[72:75], v[136:139], v[196:199], v[72:75]
	v_mfma_f32_16x16x32_bf16 v[124:127], v[132:135], v[164:167], v[124:127]
	v_mfma_f32_16x16x32_bf16 v[120:123], v[140:143], v[164:167], v[120:123]
	v_mfma_f32_16x16x32_bf16 v[108:111], v[132:135], v[172:175], v[108:111]
	v_mfma_f32_16x16x32_bf16 v[104:107], v[140:143], v[172:175], v[104:107]
	v_mfma_f32_16x16x32_bf16 v[92:95], v[132:135], v[192:195], v[92:95]
	v_mfma_f32_16x16x32_bf16 v[88:91], v[140:143], v[192:195], v[88:91]
	v_mfma_f32_16x16x32_bf16 v[76:79], v[132:135], v[200:203], v[76:79]
	v_mfma_f32_16x16x32_bf16 v[72:75], v[140:143], v[200:203], v[72:75]
	s_setprio 0
	s_setprio 1
	v_mfma_f32_16x16x32_bf16 v[116:119], v[144:147], v[160:163], v[116:119]
	v_mfma_f32_16x16x32_bf16 v[112:115], v[152:155], v[160:163], v[112:115]
	v_mfma_f32_16x16x32_bf16 v[100:103], v[144:147], v[168:171], v[100:103]
	v_mfma_f32_16x16x32_bf16 v[96:99], v[152:155], v[168:171], v[96:99]
	v_mfma_f32_16x16x32_bf16 v[84:87], v[144:147], v[188:191], v[84:87]
	v_mfma_f32_16x16x32_bf16 v[80:83], v[152:155], v[188:191], v[80:83]
	v_mfma_f32_16x16x32_bf16 v[68:71], v[144:147], v[196:199], v[68:71]
	v_mfma_f32_16x16x32_bf16 v[64:67], v[152:155], v[196:199], v[64:67]
	v_mfma_f32_16x16x32_bf16 v[116:119], v[148:151], v[164:167], v[116:119]
	v_mfma_f32_16x16x32_bf16 v[112:115], v[156:159], v[164:167], v[112:115]
	v_mfma_f32_16x16x32_bf16 v[100:103], v[148:151], v[172:175], v[100:103]
	v_mfma_f32_16x16x32_bf16 v[96:99], v[156:159], v[172:175], v[96:99]
	v_mfma_f32_16x16x32_bf16 v[84:87], v[148:151], v[192:195], v[84:87]
	v_mfma_f32_16x16x32_bf16 v[80:83], v[156:159], v[192:195], v[80:83]
	v_mfma_f32_16x16x32_bf16 v[68:71], v[148:151], v[200:203], v[68:71]
	v_mfma_f32_16x16x32_bf16 v[64:67], v[156:159], v[200:203], v[64:67]
	s_barrier
	s_setprio 0
	s_add_i32 s26, s93, s41
	v_lshl_add_u64 v[204:205], v[204:205], 0, s[10:11]
	s_mov_b32 m0, s26
	ds_read_b128 v[160:163], v213 offset:49152
	ds_read_b128 v[164:167], v213 offset:50176
	ds_read_b128 v[168:171], v213 offset:51200
	ds_read_b128 v[172:175], v213 offset:52224
	ds_read_b128 v[188:191], v213 offset:53248
	ds_read_b128 v[192:195], v213 offset:54272
	ds_read_b128 v[196:199], v213 offset:55296
	ds_read_b128 v[200:203], v213 offset:56320
	global_load_lds_dwordx4 v[204:205], off
	s_add_i32 m0, s26, 0x2000
	s_add_u32 s26, s30, 0x100080
	v_lshl_add_u64 v[204:205], v[216:217], 0, s[10:11]
	s_addc_u32 s27, s31, 0
	s_add_i32 s30, s94, s41
	global_load_lds_dwordx4 v[204:205], off
	v_lshl_add_u64 v[204:205], s[26:27], 0, v[176:177]
	s_mov_b32 m0, s30
	s_nop 0
	global_load_lds_dwordx4 v[204:205], off
	v_lshl_add_u64 v[204:205], s[26:27], 0, v[178:179]
	s_add_i32 m0, s30, 0x2000
	s_nop 0
	global_load_lds_dwordx4 v[204:205], off
	v_lshl_add_u64 v[204:205], v[218:219], 0, s[10:11]
	s_mov_b32 m0, s78
	s_nop 0
	global_load_lds_dwordx4 v[204:205], off
	v_lshl_add_u64 v[204:205], v[220:221], 0, s[10:11]
	s_mov_b32 m0, s79
	s_nop 0
	global_load_lds_dwordx4 v[204:205], off
	s_waitcnt vmcnt(8)
	s_waitcnt lgkmcnt(0)
	s_setprio 1
	s_barrier
	v_mfma_f32_16x16x32_bf16 v[60:63], v[128:131], v[160:163], v[60:63]
	v_mfma_f32_16x16x32_bf16 v[56:59], v[136:139], v[160:163], v[56:59]
	v_mfma_f32_16x16x32_bf16 v[44:47], v[128:131], v[168:171], v[44:47]
	v_mfma_f32_16x16x32_bf16 v[40:43], v[136:139], v[168:171], v[40:43]
	v_mfma_f32_16x16x32_bf16 v[28:31], v[128:131], v[188:191], v[28:31]
	v_mfma_f32_16x16x32_bf16 v[24:27], v[136:139], v[188:191], v[24:27]
	v_mfma_f32_16x16x32_bf16 v[12:15], v[128:131], v[196:199], v[12:15]
	v_mfma_f32_16x16x32_bf16 v[8:11], v[136:139], v[196:199], v[8:11]
	v_mfma_f32_16x16x32_bf16 v[60:63], v[132:135], v[164:167], v[60:63]
	v_mfma_f32_16x16x32_bf16 v[56:59], v[140:143], v[164:167], v[56:59]
	v_mfma_f32_16x16x32_bf16 v[44:47], v[132:135], v[172:175], v[44:47]
	v_mfma_f32_16x16x32_bf16 v[40:43], v[140:143], v[172:175], v[40:43]
	v_mfma_f32_16x16x32_bf16 v[28:31], v[132:135], v[192:195], v[28:31]
	v_mfma_f32_16x16x32_bf16 v[24:27], v[140:143], v[192:195], v[24:27]
	v_mfma_f32_16x16x32_bf16 v[12:15], v[132:135], v[200:203], v[12:15]
	v_mfma_f32_16x16x32_bf16 v[8:11], v[140:143], v[200:203], v[8:11]
	s_setprio 0
	s_setprio 1
	v_mfma_f32_16x16x32_bf16 v[52:55], v[144:147], v[160:163], v[52:55]
	v_mfma_f32_16x16x32_bf16 v[48:51], v[152:155], v[160:163], v[48:51]
	v_mfma_f32_16x16x32_bf16 v[36:39], v[144:147], v[168:171], v[36:39]
	v_mfma_f32_16x16x32_bf16 v[32:35], v[152:155], v[168:171], v[32:35]
	v_mfma_f32_16x16x32_bf16 v[20:23], v[144:147], v[188:191], v[20:23]
	v_mfma_f32_16x16x32_bf16 v[16:19], v[152:155], v[188:191], v[16:19]
	v_mfma_f32_16x16x32_bf16 v[4:7], v[144:147], v[196:199], v[4:7]
	v_mfma_f32_16x16x32_bf16 v[0:3], v[152:155], v[196:199], v[0:3]
	v_mfma_f32_16x16x32_bf16 v[52:55], v[148:151], v[164:167], v[52:55]
	v_mfma_f32_16x16x32_bf16 v[48:51], v[156:159], v[164:167], v[48:51]
	v_mfma_f32_16x16x32_bf16 v[36:39], v[148:151], v[172:175], v[36:39]
	v_mfma_f32_16x16x32_bf16 v[32:35], v[156:159], v[172:175], v[32:35]
	v_mfma_f32_16x16x32_bf16 v[20:23], v[148:151], v[192:195], v[20:23]
	v_mfma_f32_16x16x32_bf16 v[16:19], v[156:159], v[192:195], v[16:19]
	v_mfma_f32_16x16x32_bf16 v[4:7], v[148:151], v[200:203], v[4:7]
	v_mfma_f32_16x16x32_bf16 v[0:3], v[156:159], v[200:203], v[0:3]
	s_barrier
	s_setprio 0
	s_add_i32 s92, s92, 2
	s_add_u32 s90, s90, 0x100
	s_addc_u32 s91, s91, 0
	s_cmp_gt_u32 s92, 61
	s_mov_b64 s[26:27], s[28:29]
	s_cbranch_scc0 .LBB0_852
	s_and_b64 vcc, exec, s[12:13]
	s_cbranch_vccz .LBB0_855
	s_barrier

.LBB0_1016:
	ds_read_b128 v[144:147], v151
	ds_read_b128 v[156:159], v151 offset:1024
	ds_read_b128 v[160:163], v151 offset:2048
	ds_read_b128 v[164:167], v151 offset:3072
	ds_read_b128 v[168:171], v152
	ds_read_b128 v[172:175], v152 offset:1024
	ds_read_b128 v[176:179], v152 offset:2048
	ds_read_b128 v[180:183], v152 offset:3072
	s_add_u32 s24, s22, 0xfffc0080
	s_addc_u32 s25, s23, -1
	s_cmp_eq_u32 s52, 12
	s_cselect_b32 s27, s15, s25
	s_cselect_b32 s26, s48, s24
	s_cselect_b32 s25, s13, s51
	s_cselect_b32 s24, s49, s50
	v_lshl_add_u64 v[204:205], s[22:23], 0, v[136:137]
	s_add_i32 m0, s21, 0xc000
	ds_read_b128 v[184:187], v153
	ds_read_b128 v[188:191], v153 offset:1024
	ds_read_b128 v[192:195], v153 offset:2048
	ds_read_b128 v[196:199], v153 offset:3072
	ds_read_b128 v[200:203], v153 offset:4096
	ds_read_b128 v[208:211], v153 offset:5120
	ds_read_b128 v[212:215], v153 offset:6144
	ds_read_b128 v[216:219], v153 offset:7168
	global_load_lds_dwordx4 v[204:205], off
	v_lshl_add_u64 v[204:205], s[22:23], 0, v[138:139]
	s_add_i32 m0, s21, 0xe000
	s_nop 0
	global_load_lds_dwordx4 v[204:205], off
	s_waitcnt vmcnt(8)
	s_waitcnt lgkmcnt(0)
	s_setprio 1
	s_barrier
	v_mfma_f32_16x16x32_bf16 v[124:127], v[144:147], v[184:187], v[124:127]
	v_mfma_f32_16x16x32_bf16 v[120:123], v[160:163], v[184:187], v[120:123]
	v_mfma_f32_16x16x32_bf16 v[116:119], v[144:147], v[192:195], v[116:119]
	v_mfma_f32_16x16x32_bf16 v[112:115], v[160:163], v[192:195], v[112:115]
	v_mfma_f32_16x16x32_bf16 v[104:107], v[144:147], v[200:203], v[104:107]
	v_mfma_f32_16x16x32_bf16 v[96:99], v[160:163], v[200:203], v[96:99]
	v_mfma_f32_16x16x32_bf16 v[76:79], v[144:147], v[212:215], v[76:79]
	v_mfma_f32_16x16x32_bf16 v[72:75], v[160:163], v[212:215], v[72:75]
	v_mfma_f32_16x16x32_bf16 v[124:127], v[156:159], v[188:191], v[124:127]
	v_mfma_f32_16x16x32_bf16 v[120:123], v[164:167], v[188:191], v[120:123]
	v_mfma_f32_16x16x32_bf16 v[116:119], v[156:159], v[196:199], v[116:119]
	v_mfma_f32_16x16x32_bf16 v[112:115], v[164:167], v[196:199], v[112:115]
	v_mfma_f32_16x16x32_bf16 v[104:107], v[156:159], v[208:211], v[104:107]
	v_mfma_f32_16x16x32_bf16 v[96:99], v[164:167], v[208:211], v[96:99]
	v_mfma_f32_16x16x32_bf16 v[76:79], v[156:159], v[216:219], v[76:79]
	v_mfma_f32_16x16x32_bf16 v[72:75], v[164:167], v[216:219], v[72:75]
	s_setprio 0
	s_setprio 1
	v_mfma_f32_16x16x32_bf16 v[108:111], v[168:171], v[184:187], v[108:111]
	v_mfma_f32_16x16x32_bf16 v[100:103], v[176:179], v[184:187], v[100:103]
	v_mfma_f32_16x16x32_bf16 v[92:95], v[168:171], v[192:195], v[92:95]
	v_mfma_f32_16x16x32_bf16 v[88:91], v[176:179], v[192:195], v[88:91]
	v_mfma_f32_16x16x32_bf16 v[84:87], v[168:171], v[200:203], v[84:87]
	v_mfma_f32_16x16x32_bf16 v[80:83], v[176:179], v[200:203], v[80:83]
	v_mfma_f32_16x16x32_bf16 v[68:71], v[168:171], v[212:215], v[68:71]
	v_mfma_f32_16x16x32_bf16 v[64:67], v[176:179], v[212:215], v[64:67]
	v_mfma_f32_16x16x32_bf16 v[108:111], v[172:175], v[188:191], v[108:111]
	v_mfma_f32_16x16x32_bf16 v[100:103], v[180:183], v[188:191], v[100:103]
	v_mfma_f32_16x16x32_bf16 v[92:95], v[172:175], v[196:199], v[92:95]
	v_mfma_f32_16x16x32_bf16 v[88:91], v[180:183], v[196:199], v[88:91]
	v_mfma_f32_16x16x32_bf16 v[84:87], v[172:175], v[208:211], v[84:87]
	v_mfma_f32_16x16x32_bf16 v[80:83], v[180:183], v[208:211], v[80:83]
	v_mfma_f32_16x16x32_bf16 v[68:71], v[172:175], v[216:219], v[68:71]
	v_mfma_f32_16x16x32_bf16 v[64:67], v[180:183], v[216:219], v[64:67]
	s_barrier
	s_setprio 0
	s_add_i32 s53, s43, s33
	v_lshl_add_u64 v[204:205], s[24:25], 0, v[132:133]
	s_mov_b32 m0, s53
	ds_read_b128 v[184:187], v153 offset:16384
	ds_read_b128 v[188:191], v153 offset:17408
	ds_read_b128 v[192:195], v153 offset:18432
	ds_read_b128 v[196:199], v153 offset:19456
	ds_read_b128 v[200:203], v153 offset:20480
	ds_read_b128 v[208:211], v153 offset:21504
	ds_read_b128 v[212:215], v153 offset:22528
	ds_read_b128 v[216:219], v153 offset:23552
	global_load_lds_dwordx4 v[204:205], off
	s_add_i32 m0, s53, 0x2000
	s_add_u32 s54, s24, 0x40000
	v_lshl_add_u64 v[220:221], s[24:25], 0, v[128:129]
	s_addc_u32 s55, s25, 0
	s_add_i32 s53, s44, s33
	global_load_lds_dwordx4 v[220:221], off
	v_lshl_add_u64 v[222:223], s[54:55], 0, v[132:133]
	s_mov_b32 m0, s53
	v_lshl_add_u64 v[224:225], s[26:27], 0, v[130:131]
	global_load_lds_dwordx4 v[222:223], off
	v_lshl_add_u64 v[222:223], s[54:55], 0, v[128:129]
	s_add_i32 m0, s53, 0x2000
	s_nop 0
	global_load_lds_dwordx4 v[222:223], off
	v_lshl_add_u64 v[222:223], s[26:27], 0, v[134:135]
	s_mov_b32 m0, s21
	s_nop 0
	global_load_lds_dwordx4 v[222:223], off
	s_mov_b32 m0, s36
	s_nop 0
	global_load_lds_dwordx4 v[224:225], off
	s_waitcnt vmcnt(8)
	s_waitcnt lgkmcnt(0)
	s_setprio 1
	s_barrier
	v_mfma_f32_16x16x32_bf16 v[60:63], v[144:147], v[184:187], v[60:63]
	v_mfma_f32_16x16x32_bf16 v[56:59], v[160:163], v[184:187], v[56:59]
	v_mfma_f32_16x16x32_bf16 v[44:47], v[144:147], v[192:195], v[44:47]
	v_mfma_f32_16x16x32_bf16 v[40:43], v[160:163], v[192:195], v[40:43]
	v_mfma_f32_16x16x32_bf16 v[28:31], v[144:147], v[200:203], v[28:31]
	v_mfma_f32_16x16x32_bf16 v[24:27], v[160:163], v[200:203], v[24:27]
	v_mfma_f32_16x16x32_bf16 v[12:15], v[144:147], v[212:215], v[12:15]
	v_mfma_f32_16x16x32_bf16 v[8:11], v[160:163], v[212:215], v[8:11]
	v_mfma_f32_16x16x32_bf16 v[60:63], v[156:159], v[188:191], v[60:63]
	v_mfma_f32_16x16x32_bf16 v[56:59], v[164:167], v[188:191], v[56:59]
	v_mfma_f32_16x16x32_bf16 v[44:47], v[156:159], v[196:199], v[44:47]
	v_mfma_f32_16x16x32_bf16 v[40:43], v[164:167], v[196:199], v[40:43]
	v_mfma_f32_16x16x32_bf16 v[28:31], v[156:159], v[208:211], v[28:31]
	v_mfma_f32_16x16x32_bf16 v[24:27], v[164:167], v[208:211], v[24:27]
	v_mfma_f32_16x16x32_bf16 v[12:15], v[156:159], v[216:219], v[12:15]
	v_mfma_f32_16x16x32_bf16 v[8:11], v[164:167], v[216:219], v[8:11]
	s_setprio 0
	s_setprio 1
	v_mfma_f32_16x16x32_bf16 v[52:55], v[168:171], v[184:187], v[52:55]
	v_mfma_f32_16x16x32_bf16 v[48:51], v[176:179], v[184:187], v[48:51]
	v_mfma_f32_16x16x32_bf16 v[36:39], v[168:171], v[192:195], v[36:39]
	v_mfma_f32_16x16x32_bf16 v[32:35], v[176:179], v[192:195], v[32:35]
	v_mfma_f32_16x16x32_bf16 v[20:23], v[168:171], v[200:203], v[20:23]
	v_mfma_f32_16x16x32_bf16 v[16:19], v[176:179], v[200:203], v[16:19]
	v_mfma_f32_16x16x32_bf16 v[4:7], v[168:171], v[212:215], v[4:7]
	v_mfma_f32_16x16x32_bf16 v[0:3], v[176:179], v[212:215], v[0:3]
	v_mfma_f32_16x16x32_bf16 v[52:55], v[172:175], v[188:191], v[52:55]
	v_mfma_f32_16x16x32_bf16 v[48:51], v[180:183], v[188:191], v[48:51]
	v_mfma_f32_16x16x32_bf16 v[36:39], v[172:175], v[196:199], v[36:39]
	v_mfma_f32_16x16x32_bf16 v[32:35], v[180:183], v[196:199], v[32:35]
	v_mfma_f32_16x16x32_bf16 v[20:23], v[172:175], v[208:211], v[20:23]
	v_mfma_f32_16x16x32_bf16 v[16:19], v[180:183], v[208:211], v[16:19]
	v_mfma_f32_16x16x32_bf16 v[4:7], v[172:175], v[216:219], v[4:7]
	v_mfma_f32_16x16x32_bf16 v[0:3], v[180:183], v[216:219], v[0:3]
	s_barrier
	s_setprio 0
	s_add_i32 s53, 0, 0x18000
	s_add_i32 s54, 0, 0x1c000
	v_add_u32_e32 v164, s53, v149
	v_add_u32_e32 v180, s54, v149
	ds_read_b128 v[144:147], v164
	ds_read_b128 v[156:159], v164 offset:1024
	ds_read_b128 v[160:163], v164 offset:2048
	ds_read_b128 v[164:167], v164 offset:3072
	ds_read_b128 v[168:171], v180
	ds_read_b128 v[172:175], v180 offset:1024
	ds_read_b128 v[176:179], v180 offset:2048
	ds_read_b128 v[180:183], v180 offset:3072
	s_add_u32 s26, s26, 0x40000
	s_addc_u32 s27, s27, 0
	s_mov_b32 m0, s37
	v_lshl_add_u64 v[226:227], s[26:27], 0, v[134:135]
	ds_read_b128 v[184:187], v153 offset:32768
	ds_read_b128 v[188:191], v153 offset:33792
	ds_read_b128 v[192:195], v153 offset:34816
	ds_read_b128 v[196:199], v153 offset:35840
	ds_read_b128 v[200:203], v153 offset:36864
	ds_read_b128 v[208:211], v153 offset:37888
	ds_read_b128 v[212:215], v153 offset:38912
	ds_read_b128 v[216:219], v153 offset:39936
	global_load_lds_dwordx4 v[226:227], off
	v_lshl_add_u64 v[226:227], s[26:27], 0, v[130:131]
	s_mov_b32 m0, s38
	s_nop 0
	global_load_lds_dwordx4 v[226:227], off
	s_waitcnt vmcnt(8)
	s_waitcnt lgkmcnt(0)
	s_setprio 1
	s_barrier
	v_mfma_f32_16x16x32_bf16 v[124:127], v[144:147], v[184:187], v[124:127]
	v_mfma_f32_16x16x32_bf16 v[120:123], v[160:163], v[184:187], v[120:123]
	v_mfma_f32_16x16x32_bf16 v[116:119], v[144:147], v[192:195], v[116:119]
	v_mfma_f32_16x16x32_bf16 v[112:115], v[160:163], v[192:195], v[112:115]
	v_mfma_f32_16x16x32_bf16 v[104:107], v[144:147], v[200:203], v[104:107]
	v_mfma_f32_16x16x32_bf16 v[96:99], v[160:163], v[200:203], v[96:99]
	v_mfma_f32_16x16x32_bf16 v[76:79], v[144:147], v[212:215], v[76:79]
	v_mfma_f32_16x16x32_bf16 v[72:75], v[160:163], v[212:215], v[72:75]
	v_mfma_f32_16x16x32_bf16 v[124:127], v[156:159], v[188:191], v[124:127]
	v_mfma_f32_16x16x32_bf16 v[120:123], v[164:167], v[188:191], v[120:123]
	v_mfma_f32_16x16x32_bf16 v[116:119], v[156:159], v[196:199], v[116:119]
	v_mfma_f32_16x16x32_bf16 v[112:115], v[164:167], v[196:199], v[112:115]
	v_mfma_f32_16x16x32_bf16 v[104:107], v[156:159], v[208:211], v[104:107]
	v_mfma_f32_16x16x32_bf16 v[96:99], v[164:167], v[208:211], v[96:99]
	v_mfma_f32_16x16x32_bf16 v[76:79], v[156:159], v[216:219], v[76:79]
	v_mfma_f32_16x16x32_bf16 v[72:75], v[164:167], v[216:219], v[72:75]
	s_setprio 0
	s_setprio 1
	v_mfma_f32_16x16x32_bf16 v[108:111], v[168:171], v[184:187], v[108:111]
	v_mfma_f32_16x16x32_bf16 v[100:103], v[176:179], v[184:187], v[100:103]
	v_mfma_f32_16x16x32_bf16 v[92:95], v[168:171], v[192:195], v[92:95]
	v_mfma_f32_16x16x32_bf16 v[88:91], v[176:179], v[192:195], v[88:91]
	v_mfma_f32_16x16x32_bf16 v[84:87], v[168:171], v[200:203], v[84:87]
	v_mfma_f32_16x16x32_bf16 v[80:83], v[176:179], v[200:203], v[80:83]
	v_mfma_f32_16x16x32_bf16 v[68:71], v[168:171], v[212:215], v[68:71]
	v_mfma_f32_16x16x32_bf16 v[64:67], v[176:179], v[212:215], v[64:67]
	v_mfma_f32_16x16x32_bf16 v[108:111], v[172:175], v[188:191], v[108:111]
	v_mfma_f32_16x16x32_bf16 v[100:103], v[180:183], v[188:191], v[100:103]
	v_mfma_f32_16x16x32_bf16 v[92:95], v[172:175], v[196:199], v[92:95]
	v_mfma_f32_16x16x32_bf16 v[88:91], v[180:183], v[196:199], v[88:91]
	v_mfma_f32_16x16x32_bf16 v[84:87], v[172:175], v[208:211], v[84:87]
	v_mfma_f32_16x16x32_bf16 v[80:83], v[180:183], v[208:211], v[80:83]
	v_mfma_f32_16x16x32_bf16 v[68:71], v[172:175], v[216:219], v[68:71]
	v_mfma_f32_16x16x32_bf16 v[64:67], v[180:183], v[216:219], v[64:67]
	s_barrier
	s_setprio 0
	s_add_i32 s26, s53, s33
	v_lshl_add_u64 v[204:205], v[204:205], 0, s[8:9]
	s_mov_b32 m0, s26
	ds_read_b128 v[184:187], v153 offset:49152
	ds_read_b128 v[188:191], v153 offset:50176
	ds_read_b128 v[192:195], v153 offset:51200
	ds_read_b128 v[196:199], v153 offset:52224
	ds_read_b128 v[200:203], v153 offset:53248
	ds_read_b128 v[208:211], v153 offset:54272
	ds_read_b128 v[212:215], v153 offset:55296
	ds_read_b128 v[216:219], v153 offset:56320
	global_load_lds_dwordx4 v[204:205], off
	s_add_i32 m0, s26, 0x2000
	s_add_u32 s24, s24, 0x40080
	v_lshl_add_u64 v[204:205], v[220:221], 0, s[8:9]
	s_addc_u32 s25, s25, 0
	s_add_i32 s26, s54, s33
	global_load_lds_dwordx4 v[204:205], off
	v_lshl_add_u64 v[204:205], s[24:25], 0, v[132:133]
	s_mov_b32 m0, s26
	s_nop 0
	global_load_lds_dwordx4 v[204:205], off
	v_lshl_add_u64 v[204:205], s[24:25], 0, v[128:129]
	s_add_i32 m0, s26, 0x2000
	s_nop 0
	global_load_lds_dwordx4 v[204:205], off
	v_lshl_add_u64 v[204:205], v[222:223], 0, s[8:9]
	s_mov_b32 m0, s40
	s_nop 0
	global_load_lds_dwordx4 v[204:205], off
	v_lshl_add_u64 v[204:205], v[224:225], 0, s[8:9]
	s_mov_b32 m0, s41
	s_nop 0
	global_load_lds_dwordx4 v[204:205], off
	s_waitcnt vmcnt(8)
	s_waitcnt lgkmcnt(0)
	s_setprio 1
	s_barrier
	v_mfma_f32_16x16x32_bf16 v[60:63], v[144:147], v[184:187], v[60:63]
	v_mfma_f32_16x16x32_bf16 v[56:59], v[160:163], v[184:187], v[56:59]
	v_mfma_f32_16x16x32_bf16 v[44:47], v[144:147], v[192:195], v[44:47]
	v_mfma_f32_16x16x32_bf16 v[40:43], v[160:163], v[192:195], v[40:43]
	v_mfma_f32_16x16x32_bf16 v[28:31], v[144:147], v[200:203], v[28:31]
	v_mfma_f32_16x16x32_bf16 v[24:27], v[160:163], v[200:203], v[24:27]
	v_mfma_f32_16x16x32_bf16 v[12:15], v[144:147], v[212:215], v[12:15]
	v_mfma_f32_16x16x32_bf16 v[8:11], v[160:163], v[212:215], v[8:11]
	v_mfma_f32_16x16x32_bf16 v[60:63], v[156:159], v[188:191], v[60:63]
	v_mfma_f32_16x16x32_bf16 v[56:59], v[164:167], v[188:191], v[56:59]
	v_mfma_f32_16x16x32_bf16 v[44:47], v[156:159], v[196:199], v[44:47]
	v_mfma_f32_16x16x32_bf16 v[40:43], v[164:167], v[196:199], v[40:43]
	v_mfma_f32_16x16x32_bf16 v[28:31], v[156:159], v[208:211], v[28:31]
	v_mfma_f32_16x16x32_bf16 v[24:27], v[164:167], v[208:211], v[24:27]
	v_mfma_f32_16x16x32_bf16 v[12:15], v[156:159], v[216:219], v[12:15]
	v_mfma_f32_16x16x32_bf16 v[8:11], v[164:167], v[216:219], v[8:11]
	s_setprio 0
	s_setprio 1
	v_mfma_f32_16x16x32_bf16 v[52:55], v[168:171], v[184:187], v[52:55]
	v_mfma_f32_16x16x32_bf16 v[48:51], v[176:179], v[184:187], v[48:51]
	v_mfma_f32_16x16x32_bf16 v[36:39], v[168:171], v[192:195], v[36:39]
	v_mfma_f32_16x16x32_bf16 v[32:35], v[176:179], v[192:195], v[32:35]
	v_mfma_f32_16x16x32_bf16 v[20:23], v[168:171], v[200:203], v[20:23]
	v_mfma_f32_16x16x32_bf16 v[16:19], v[176:179], v[200:203], v[16:19]
	v_mfma_f32_16x16x32_bf16 v[4:7], v[168:171], v[212:215], v[4:7]
	v_mfma_f32_16x16x32_bf16 v[0:3], v[176:179], v[212:215], v[0:3]
	v_mfma_f32_16x16x32_bf16 v[52:55], v[172:175], v[188:191], v[52:55]
	v_mfma_f32_16x16x32_bf16 v[48:51], v[180:183], v[188:191], v[48:51]
	v_mfma_f32_16x16x32_bf16 v[36:39], v[172:175], v[196:199], v[36:39]
	v_mfma_f32_16x16x32_bf16 v[32:35], v[180:183], v[196:199], v[32:35]
	v_mfma_f32_16x16x32_bf16 v[20:23], v[172:175], v[208:211], v[20:23]
	v_mfma_f32_16x16x32_bf16 v[16:19], v[180:183], v[208:211], v[16:19]
	v_mfma_f32_16x16x32_bf16 v[4:7], v[172:175], v[216:219], v[4:7]
	v_mfma_f32_16x16x32_bf16 v[0:3], v[180:183], v[216:219], v[0:3]
	s_barrier
	s_setprio 0
	s_add_i32 s52, s52, 2
	s_add_u32 s22, s22, 0x100
	s_addc_u32 s23, s23, 0
	s_add_u32 s50, s50, 0x100
	s_addc_u32 s51, s51, 0
	s_cmp_gt_u32 s52, 13
	s_cbranch_scc0 .LBB0_1016
	s_and_b64 vcc, exec, s[10:11]
	s_cbranch_vccz .LBB0_1019
	s_barrier

.LBB0_1218:
	ds_read_b128 v[128:131], v212
	ds_read_b128 v[132:135], v212 offset:1024
	ds_read_b128 v[136:139], v212 offset:2048
	ds_read_b128 v[140:143], v212 offset:3072
	ds_read_b128 v[144:147], v213
	ds_read_b128 v[148:151], v213 offset:1024
	ds_read_b128 v[152:155], v213 offset:2048
	ds_read_b128 v[156:159], v213 offset:3072
	s_add_u32 s28, s26, 0x100
	s_addc_u32 s29, s27, 0
	s_cmp_eq_u32 s54, 12
	s_cselect_b32 s35, s3, s29
	s_cselect_b32 s34, s17, s28
	s_cselect_b32 s31, s15, s53
	s_cselect_b32 s30, s23, s52
	v_lshl_add_u64 v[204:205], s[26:27], 0, v[180:181]
	s_add_i32 m0, s25, 0xc000
	ds_read_b128 v[160:163], v214
	ds_read_b128 v[164:167], v214 offset:1024
	ds_read_b128 v[168:171], v214 offset:2048
	ds_read_b128 v[172:175], v214 offset:3072
	ds_read_b128 v[188:191], v214 offset:4096
	ds_read_b128 v[192:195], v214 offset:5120
	ds_read_b128 v[196:199], v214 offset:6144
	ds_read_b128 v[200:203], v214 offset:7168
	global_load_lds_dwordx4 v[204:205], off
	v_lshl_add_u64 v[204:205], s[26:27], 0, v[182:183]
	s_add_i32 m0, s25, 0xe000
	s_nop 0
	global_load_lds_dwordx4 v[204:205], off
	s_waitcnt vmcnt(8)
	s_waitcnt lgkmcnt(0)
	s_setprio 1
	s_barrier
	v_mfma_f32_16x16x32_bf16 v[124:127], v[128:131], v[160:163], v[124:127]
	v_mfma_f32_16x16x32_bf16 v[120:123], v[136:139], v[160:163], v[120:123]
	v_mfma_f32_16x16x32_bf16 v[108:111], v[128:131], v[168:171], v[108:111]
	v_mfma_f32_16x16x32_bf16 v[104:107], v[136:139], v[168:171], v[104:107]
	v_mfma_f32_16x16x32_bf16 v[92:95], v[128:131], v[188:191], v[92:95]
	v_mfma_f32_16x16x32_bf16 v[88:91], v[136:139], v[188:191], v[88:91]
	v_mfma_f32_16x16x32_bf16 v[76:79], v[128:131], v[196:199], v[76:79]
	v_mfma_f32_16x16x32_bf16 v[72:75], v[136:139], v[196:199], v[72:75]
	v_mfma_f32_16x16x32_bf16 v[124:127], v[132:135], v[164:167], v[124:127]
	v_mfma_f32_16x16x32_bf16 v[120:123], v[140:143], v[164:167], v[120:123]
	v_mfma_f32_16x16x32_bf16 v[108:111], v[132:135], v[172:175], v[108:111]
	v_mfma_f32_16x16x32_bf16 v[104:107], v[140:143], v[172:175], v[104:107]
	v_mfma_f32_16x16x32_bf16 v[92:95], v[132:135], v[192:195], v[92:95]
	v_mfma_f32_16x16x32_bf16 v[88:91], v[140:143], v[192:195], v[88:91]
	v_mfma_f32_16x16x32_bf16 v[76:79], v[132:135], v[200:203], v[76:79]
	v_mfma_f32_16x16x32_bf16 v[72:75], v[140:143], v[200:203], v[72:75]
	s_setprio 0
	s_setprio 1
	v_mfma_f32_16x16x32_bf16 v[116:119], v[144:147], v[160:163], v[116:119]
	v_mfma_f32_16x16x32_bf16 v[112:115], v[152:155], v[160:163], v[112:115]
	v_mfma_f32_16x16x32_bf16 v[100:103], v[144:147], v[168:171], v[100:103]
	v_mfma_f32_16x16x32_bf16 v[96:99], v[152:155], v[168:171], v[96:99]
	v_mfma_f32_16x16x32_bf16 v[84:87], v[144:147], v[188:191], v[84:87]
	v_mfma_f32_16x16x32_bf16 v[80:83], v[152:155], v[188:191], v[80:83]
	v_mfma_f32_16x16x32_bf16 v[68:71], v[144:147], v[196:199], v[68:71]
	v_mfma_f32_16x16x32_bf16 v[64:67], v[152:155], v[196:199], v[64:67]
	v_mfma_f32_16x16x32_bf16 v[116:119], v[148:151], v[164:167], v[116:119]
	v_mfma_f32_16x16x32_bf16 v[112:115], v[156:159], v[164:167], v[112:115]
	v_mfma_f32_16x16x32_bf16 v[100:103], v[148:151], v[172:175], v[100:103]
	v_mfma_f32_16x16x32_bf16 v[96:99], v[156:159], v[172:175], v[96:99]
	v_mfma_f32_16x16x32_bf16 v[84:87], v[148:151], v[192:195], v[84:87]
	v_mfma_f32_16x16x32_bf16 v[80:83], v[156:159], v[192:195], v[80:83]
	v_mfma_f32_16x16x32_bf16 v[68:71], v[148:151], v[200:203], v[68:71]
	v_mfma_f32_16x16x32_bf16 v[64:67], v[156:159], v[200:203], v[64:67]
	s_barrier
	s_setprio 0
	s_add_i32 s26, s50, s39
	v_lshl_add_u64 v[204:205], s[30:31], 0, v[176:177]
	s_mov_b32 m0, s26
	ds_read_b128 v[160:163], v214 offset:16384
	ds_read_b128 v[164:167], v214 offset:17408
	ds_read_b128 v[168:171], v214 offset:18432
	ds_read_b128 v[172:175], v214 offset:19456
	ds_read_b128 v[188:191], v214 offset:20480
	ds_read_b128 v[192:195], v214 offset:21504
	ds_read_b128 v[196:199], v214 offset:22528
	ds_read_b128 v[200:203], v214 offset:23552
	global_load_lds_dwordx4 v[204:205], off
	s_add_i32 m0, s26, 0x2000
	s_add_u32 s26, s30, 0x40000
	v_lshl_add_u64 v[216:217], s[30:31], 0, v[178:179]
	s_addc_u32 s27, s31, 0
	s_add_i32 s55, s51, s39
	global_load_lds_dwordx4 v[216:217], off
	v_lshl_add_u64 v[218:219], s[26:27], 0, v[176:177]
	s_mov_b32 m0, s55
	v_lshl_add_u64 v[220:221], s[34:35], 0, v[178:179]
	global_load_lds_dwordx4 v[218:219], off
	v_lshl_add_u64 v[218:219], s[26:27], 0, v[178:179]
	s_add_i32 m0, s55, 0x2000
	s_nop 0
	global_load_lds_dwordx4 v[218:219], off
	v_lshl_add_u64 v[218:219], s[34:35], 0, v[176:177]
	s_mov_b32 m0, s25
	s_nop 0
	global_load_lds_dwordx4 v[218:219], off
	s_mov_b32 m0, s40
	s_nop 0
	global_load_lds_dwordx4 v[220:221], off
	s_waitcnt vmcnt(8)
	s_waitcnt lgkmcnt(0)
	s_setprio 1
	s_barrier
	v_mfma_f32_16x16x32_bf16 v[60:63], v[128:131], v[160:163], v[60:63]
	v_mfma_f32_16x16x32_bf16 v[56:59], v[136:139], v[160:163], v[56:59]
	v_mfma_f32_16x16x32_bf16 v[44:47], v[128:131], v[168:171], v[44:47]
	v_mfma_f32_16x16x32_bf16 v[40:43], v[136:139], v[168:171], v[40:43]
	v_mfma_f32_16x16x32_bf16 v[28:31], v[128:131], v[188:191], v[28:31]
	v_mfma_f32_16x16x32_bf16 v[24:27], v[136:139], v[188:191], v[24:27]
	v_mfma_f32_16x16x32_bf16 v[12:15], v[128:131], v[196:199], v[12:15]
	v_mfma_f32_16x16x32_bf16 v[8:11], v[136:139], v[196:199], v[8:11]
	v_mfma_f32_16x16x32_bf16 v[60:63], v[132:135], v[164:167], v[60:63]
	v_mfma_f32_16x16x32_bf16 v[56:59], v[140:143], v[164:167], v[56:59]
	v_mfma_f32_16x16x32_bf16 v[44:47], v[132:135], v[172:175], v[44:47]
	v_mfma_f32_16x16x32_bf16 v[40:43], v[140:143], v[172:175], v[40:43]
	v_mfma_f32_16x16x32_bf16 v[28:31], v[132:135], v[192:195], v[28:31]
	v_mfma_f32_16x16x32_bf16 v[24:27], v[140:143], v[192:195], v[24:27]
	v_mfma_f32_16x16x32_bf16 v[12:15], v[132:135], v[200:203], v[12:15]
	v_mfma_f32_16x16x32_bf16 v[8:11], v[140:143], v[200:203], v[8:11]
	s_setprio 0
	s_setprio 1
	v_mfma_f32_16x16x32_bf16 v[52:55], v[144:147], v[160:163], v[52:55]
	v_mfma_f32_16x16x32_bf16 v[48:51], v[152:155], v[160:163], v[48:51]
	v_mfma_f32_16x16x32_bf16 v[36:39], v[144:147], v[168:171], v[36:39]
	v_mfma_f32_16x16x32_bf16 v[32:35], v[152:155], v[168:171], v[32:35]
	v_mfma_f32_16x16x32_bf16 v[20:23], v[144:147], v[188:191], v[20:23]
	v_mfma_f32_16x16x32_bf16 v[16:19], v[152:155], v[188:191], v[16:19]
	v_mfma_f32_16x16x32_bf16 v[4:7], v[144:147], v[196:199], v[4:7]
	v_mfma_f32_16x16x32_bf16 v[0:3], v[152:155], v[196:199], v[0:3]
	v_mfma_f32_16x16x32_bf16 v[52:55], v[148:151], v[164:167], v[52:55]
	v_mfma_f32_16x16x32_bf16 v[48:51], v[156:159], v[164:167], v[48:51]
	v_mfma_f32_16x16x32_bf16 v[36:39], v[148:151], v[172:175], v[36:39]
	v_mfma_f32_16x16x32_bf16 v[32:35], v[156:159], v[172:175], v[32:35]
	v_mfma_f32_16x16x32_bf16 v[20:23], v[148:151], v[192:195], v[20:23]
	v_mfma_f32_16x16x32_bf16 v[16:19], v[156:159], v[192:195], v[16:19]
	v_mfma_f32_16x16x32_bf16 v[4:7], v[148:151], v[200:203], v[4:7]
	v_mfma_f32_16x16x32_bf16 v[0:3], v[156:159], v[200:203], v[0:3]
	s_barrier
	s_setprio 0
	s_add_i32 s55, 0, 0x18000
	s_add_i32 s56, 0, 0x1c000
	v_add_u32_e32 v140, s55, v210
	v_add_u32_e32 v156, s56, v210
	ds_read_b128 v[128:131], v140
	ds_read_b128 v[132:135], v140 offset:1024
	ds_read_b128 v[136:139], v140 offset:2048
	ds_read_b128 v[140:143], v140 offset:3072
	ds_read_b128 v[144:147], v156
	ds_read_b128 v[148:151], v156 offset:1024
	ds_read_b128 v[152:155], v156 offset:2048
	ds_read_b128 v[156:159], v156 offset:3072
	s_add_u32 s26, s34, 0x40000
	s_addc_u32 s27, s35, 0
	s_mov_b32 m0, s41
	v_lshl_add_u64 v[222:223], s[26:27], 0, v[176:177]
	ds_read_b128 v[160:163], v214 offset:32768
	ds_read_b128 v[164:167], v214 offset:33792
	ds_read_b128 v[168:171], v214 offset:34816
	ds_read_b128 v[172:175], v214 offset:35840
	ds_read_b128 v[188:191], v214 offset:36864
	ds_read_b128 v[192:195], v214 offset:37888
	ds_read_b128 v[196:199], v214 offset:38912
	ds_read_b128 v[200:203], v214 offset:39936
	global_load_lds_dwordx4 v[222:223], off
	v_lshl_add_u64 v[222:223], s[26:27], 0, v[178:179]
	s_mov_b32 m0, s42
	s_nop 0
	global_load_lds_dwordx4 v[222:223], off
	s_waitcnt vmcnt(8)
	s_waitcnt lgkmcnt(0)
	s_setprio 1
	s_barrier
	v_mfma_f32_16x16x32_bf16 v[124:127], v[128:131], v[160:163], v[124:127]
	v_mfma_f32_16x16x32_bf16 v[120:123], v[136:139], v[160:163], v[120:123]
	v_mfma_f32_16x16x32_bf16 v[108:111], v[128:131], v[168:171], v[108:111]
	v_mfma_f32_16x16x32_bf16 v[104:107], v[136:139], v[168:171], v[104:107]
	v_mfma_f32_16x16x32_bf16 v[92:95], v[128:131], v[188:191], v[92:95]
	v_mfma_f32_16x16x32_bf16 v[88:91], v[136:139], v[188:191], v[88:91]
	v_mfma_f32_16x16x32_bf16 v[76:79], v[128:131], v[196:199], v[76:79]
	v_mfma_f32_16x16x32_bf16 v[72:75], v[136:139], v[196:199], v[72:75]
	v_mfma_f32_16x16x32_bf16 v[124:127], v[132:135], v[164:167], v[124:127]
	v_mfma_f32_16x16x32_bf16 v[120:123], v[140:143], v[164:167], v[120:123]
	v_mfma_f32_16x16x32_bf16 v[108:111], v[132:135], v[172:175], v[108:111]
	v_mfma_f32_16x16x32_bf16 v[104:107], v[140:143], v[172:175], v[104:107]
	v_mfma_f32_16x16x32_bf16 v[92:95], v[132:135], v[192:195], v[92:95]
	v_mfma_f32_16x16x32_bf16 v[88:91], v[140:143], v[192:195], v[88:91]
	v_mfma_f32_16x16x32_bf16 v[76:79], v[132:135], v[200:203], v[76:79]
	v_mfma_f32_16x16x32_bf16 v[72:75], v[140:143], v[200:203], v[72:75]
	s_setprio 0
	s_setprio 1
	v_mfma_f32_16x16x32_bf16 v[116:119], v[144:147], v[160:163], v[116:119]
	v_mfma_f32_16x16x32_bf16 v[112:115], v[152:155], v[160:163], v[112:115]
	v_mfma_f32_16x16x32_bf16 v[100:103], v[144:147], v[168:171], v[100:103]
	v_mfma_f32_16x16x32_bf16 v[96:99], v[152:155], v[168:171], v[96:99]
	v_mfma_f32_16x16x32_bf16 v[84:87], v[144:147], v[188:191], v[84:87]
	v_mfma_f32_16x16x32_bf16 v[80:83], v[152:155], v[188:191], v[80:83]
	v_mfma_f32_16x16x32_bf16 v[68:71], v[144:147], v[196:199], v[68:71]
	v_mfma_f32_16x16x32_bf16 v[64:67], v[152:155], v[196:199], v[64:67]
	v_mfma_f32_16x16x32_bf16 v[116:119], v[148:151], v[164:167], v[116:119]
	v_mfma_f32_16x16x32_bf16 v[112:115], v[156:159], v[164:167], v[112:115]
	v_mfma_f32_16x16x32_bf16 v[100:103], v[148:151], v[172:175], v[100:103]
	v_mfma_f32_16x16x32_bf16 v[96:99], v[156:159], v[172:175], v[96:99]
	v_mfma_f32_16x16x32_bf16 v[84:87], v[148:151], v[192:195], v[84:87]
	v_mfma_f32_16x16x32_bf16 v[80:83], v[156:159], v[192:195], v[80:83]
	v_mfma_f32_16x16x32_bf16 v[68:71], v[148:151], v[200:203], v[68:71]
	v_mfma_f32_16x16x32_bf16 v[64:67], v[156:159], v[200:203], v[64:67]
	s_barrier
	s_setprio 0
	s_add_i32 s26, s55, s39
	v_lshl_add_u64 v[204:205], v[204:205], 0, s[10:11]
	s_mov_b32 m0, s26
	ds_read_b128 v[160:163], v214 offset:49152
	ds_read_b128 v[164:167], v214 offset:50176
	ds_read_b128 v[168:171], v214 offset:51200
	ds_read_b128 v[172:175], v214 offset:52224
	ds_read_b128 v[188:191], v214 offset:53248
	ds_read_b128 v[192:195], v214 offset:54272
	ds_read_b128 v[196:199], v214 offset:55296
	ds_read_b128 v[200:203], v214 offset:56320
	global_load_lds_dwordx4 v[204:205], off
	s_add_i32 m0, s26, 0x2000
	s_add_u32 s26, s30, 0x40080
	v_lshl_add_u64 v[204:205], v[216:217], 0, s[10:11]
	s_addc_u32 s27, s31, 0
	s_add_i32 s30, s56, s39
	global_load_lds_dwordx4 v[204:205], off
	v_lshl_add_u64 v[204:205], s[26:27], 0, v[176:177]
	s_mov_b32 m0, s30
	s_nop 0
	global_load_lds_dwordx4 v[204:205], off
	v_lshl_add_u64 v[204:205], s[26:27], 0, v[178:179]
	s_add_i32 m0, s30, 0x2000
	s_nop 0
	global_load_lds_dwordx4 v[204:205], off
	v_lshl_add_u64 v[204:205], v[218:219], 0, s[10:11]
	s_mov_b32 m0, s44
	s_nop 0
	global_load_lds_dwordx4 v[204:205], off
	v_lshl_add_u64 v[204:205], v[220:221], 0, s[10:11]
	s_mov_b32 m0, s45
	s_nop 0
	global_load_lds_dwordx4 v[204:205], off
	s_waitcnt vmcnt(8)
	s_waitcnt lgkmcnt(0)
	s_setprio 1
	s_barrier
	v_mfma_f32_16x16x32_bf16 v[60:63], v[128:131], v[160:163], v[60:63]
	v_mfma_f32_16x16x32_bf16 v[56:59], v[136:139], v[160:163], v[56:59]
	v_mfma_f32_16x16x32_bf16 v[44:47], v[128:131], v[168:171], v[44:47]
	v_mfma_f32_16x16x32_bf16 v[40:43], v[136:139], v[168:171], v[40:43]
	v_mfma_f32_16x16x32_bf16 v[28:31], v[128:131], v[188:191], v[28:31]
	v_mfma_f32_16x16x32_bf16 v[24:27], v[136:139], v[188:191], v[24:27]
	v_mfma_f32_16x16x32_bf16 v[12:15], v[128:131], v[196:199], v[12:15]
	v_mfma_f32_16x16x32_bf16 v[8:11], v[136:139], v[196:199], v[8:11]
	v_mfma_f32_16x16x32_bf16 v[60:63], v[132:135], v[164:167], v[60:63]
	v_mfma_f32_16x16x32_bf16 v[56:59], v[140:143], v[164:167], v[56:59]
	v_mfma_f32_16x16x32_bf16 v[44:47], v[132:135], v[172:175], v[44:47]
	v_mfma_f32_16x16x32_bf16 v[40:43], v[140:143], v[172:175], v[40:43]
	v_mfma_f32_16x16x32_bf16 v[28:31], v[132:135], v[192:195], v[28:31]
	v_mfma_f32_16x16x32_bf16 v[24:27], v[140:143], v[192:195], v[24:27]
	v_mfma_f32_16x16x32_bf16 v[12:15], v[132:135], v[200:203], v[12:15]
	v_mfma_f32_16x16x32_bf16 v[8:11], v[140:143], v[200:203], v[8:11]
	s_setprio 0
	s_setprio 1
	v_mfma_f32_16x16x32_bf16 v[52:55], v[144:147], v[160:163], v[52:55]
	v_mfma_f32_16x16x32_bf16 v[48:51], v[152:155], v[160:163], v[48:51]
	v_mfma_f32_16x16x32_bf16 v[36:39], v[144:147], v[168:171], v[36:39]
	v_mfma_f32_16x16x32_bf16 v[32:35], v[152:155], v[168:171], v[32:35]
	v_mfma_f32_16x16x32_bf16 v[20:23], v[144:147], v[188:191], v[20:23]
	v_mfma_f32_16x16x32_bf16 v[16:19], v[152:155], v[188:191], v[16:19]
	v_mfma_f32_16x16x32_bf16 v[4:7], v[144:147], v[196:199], v[4:7]
	v_mfma_f32_16x16x32_bf16 v[0:3], v[152:155], v[196:199], v[0:3]
	v_mfma_f32_16x16x32_bf16 v[52:55], v[148:151], v[164:167], v[52:55]
	v_mfma_f32_16x16x32_bf16 v[48:51], v[156:159], v[164:167], v[48:51]
	v_mfma_f32_16x16x32_bf16 v[36:39], v[148:151], v[172:175], v[36:39]
	v_mfma_f32_16x16x32_bf16 v[32:35], v[156:159], v[172:175], v[32:35]
	v_mfma_f32_16x16x32_bf16 v[20:23], v[148:151], v[192:195], v[20:23]
	v_mfma_f32_16x16x32_bf16 v[16:19], v[156:159], v[192:195], v[16:19]
	v_mfma_f32_16x16x32_bf16 v[4:7], v[148:151], v[200:203], v[4:7]
	v_mfma_f32_16x16x32_bf16 v[0:3], v[156:159], v[200:203], v[0:3]
	s_barrier
	s_setprio 0
	s_add_i32 s54, s54, 2
	s_add_u32 s52, s52, 0x100
	s_addc_u32 s53, s53, 0
	s_cmp_gt_u32 s54, 13
	s_mov_b64 s[26:27], s[28:29]
	s_cbranch_scc0 .LBB0_1218
	s_and_b64 vcc, exec, s[12:13]
	s_cbranch_vccz .LBB0_1221
	s_barrier

.LBB0_1310:
	ds_read_b128 v[144:147], v155
	ds_read_b128 v[148:151], v155 offset:1024
	ds_read_b128 v[160:163], v155 offset:2048
	ds_read_b128 v[164:167], v155 offset:3072
	ds_read_b128 v[168:171], v156
	ds_read_b128 v[172:175], v156 offset:1024
	ds_read_b128 v[176:179], v156 offset:2048
	ds_read_b128 v[180:183], v156 offset:3072
	s_add_u32 s34, s30, 0xfffc0080
	s_addc_u32 s35, s31, -1
	s_cmp_eq_u32 s62, 12
	s_cselect_b32 s37, s23, s35
	s_cselect_b32 s36, s58, s34
	s_cselect_b32 s35, s21, s61
	s_cselect_b32 s34, s59, s60
	v_lshl_add_u64 v[204:205], s[30:31], 0, v[136:137]
	s_add_i32 m0, s29, 0xc000
	ds_read_b128 v[184:187], v157
	ds_read_b128 v[188:191], v157 offset:1024
	ds_read_b128 v[192:195], v157 offset:2048
	ds_read_b128 v[196:199], v157 offset:3072
	ds_read_b128 v[200:203], v157 offset:4096
	ds_read_b128 v[210:213], v157 offset:5120
	ds_read_b128 v[214:217], v157 offset:6144
	ds_read_b128 v[218:221], v157 offset:7168
	global_load_lds_dwordx4 v[204:205], off
	v_lshl_add_u64 v[204:205], s[30:31], 0, v[138:139]
	s_add_i32 m0, s29, 0xe000
	s_nop 0
	global_load_lds_dwordx4 v[204:205], off
	s_waitcnt vmcnt(8)
	s_waitcnt lgkmcnt(0)
	s_setprio 1
	s_barrier
	v_mfma_f32_16x16x32_bf16 v[124:127], v[144:147], v[184:187], v[124:127]
	v_mfma_f32_16x16x32_bf16 v[120:123], v[160:163], v[184:187], v[120:123]
	v_mfma_f32_16x16x32_bf16 v[116:119], v[144:147], v[192:195], v[116:119]
	v_mfma_f32_16x16x32_bf16 v[104:107], v[160:163], v[192:195], v[104:107]
	v_mfma_f32_16x16x32_bf16 v[92:95], v[144:147], v[200:203], v[92:95]
	v_mfma_f32_16x16x32_bf16 v[88:91], v[160:163], v[200:203], v[88:91]
	v_mfma_f32_16x16x32_bf16 v[76:79], v[144:147], v[214:217], v[76:79]
	v_mfma_f32_16x16x32_bf16 v[72:75], v[160:163], v[214:217], v[72:75]
	v_mfma_f32_16x16x32_bf16 v[124:127], v[148:151], v[188:191], v[124:127]
	v_mfma_f32_16x16x32_bf16 v[120:123], v[164:167], v[188:191], v[120:123]
	v_mfma_f32_16x16x32_bf16 v[116:119], v[148:151], v[196:199], v[116:119]
	v_mfma_f32_16x16x32_bf16 v[104:107], v[164:167], v[196:199], v[104:107]
	v_mfma_f32_16x16x32_bf16 v[92:95], v[148:151], v[210:213], v[92:95]
	v_mfma_f32_16x16x32_bf16 v[88:91], v[164:167], v[210:213], v[88:91]
	v_mfma_f32_16x16x32_bf16 v[76:79], v[148:151], v[218:221], v[76:79]
	v_mfma_f32_16x16x32_bf16 v[72:75], v[164:167], v[218:221], v[72:75]
	s_setprio 0
	s_setprio 1
	v_mfma_f32_16x16x32_bf16 v[112:115], v[168:171], v[184:187], v[112:115]
	v_mfma_f32_16x16x32_bf16 v[108:111], v[176:179], v[184:187], v[108:111]
	v_mfma_f32_16x16x32_bf16 v[100:103], v[168:171], v[192:195], v[100:103]
	v_mfma_f32_16x16x32_bf16 v[96:99], v[176:179], v[192:195], v[96:99]
	v_mfma_f32_16x16x32_bf16 v[84:87], v[168:171], v[200:203], v[84:87]
	v_mfma_f32_16x16x32_bf16 v[80:83], v[176:179], v[200:203], v[80:83]
	v_mfma_f32_16x16x32_bf16 v[68:71], v[168:171], v[214:217], v[68:71]
	v_mfma_f32_16x16x32_bf16 v[64:67], v[176:179], v[214:217], v[64:67]
	v_mfma_f32_16x16x32_bf16 v[112:115], v[172:175], v[188:191], v[112:115]
	v_mfma_f32_16x16x32_bf16 v[108:111], v[180:183], v[188:191], v[108:111]
	v_mfma_f32_16x16x32_bf16 v[100:103], v[172:175], v[196:199], v[100:103]
	v_mfma_f32_16x16x32_bf16 v[96:99], v[180:183], v[196:199], v[96:99]
	v_mfma_f32_16x16x32_bf16 v[84:87], v[172:175], v[210:213], v[84:87]
	v_mfma_f32_16x16x32_bf16 v[80:83], v[180:183], v[210:213], v[80:83]
	v_mfma_f32_16x16x32_bf16 v[68:71], v[172:175], v[218:221], v[68:71]
	v_mfma_f32_16x16x32_bf16 v[64:67], v[180:183], v[218:221], v[64:67]
	s_barrier
	s_setprio 0
	s_add_i32 s63, s52, s42
	v_lshl_add_u64 v[204:205], s[34:35], 0, v[130:131]
	s_mov_b32 m0, s63
	ds_read_b128 v[184:187], v157 offset:16384
	ds_read_b128 v[188:191], v157 offset:17408
	ds_read_b128 v[192:195], v157 offset:18432
	ds_read_b128 v[196:199], v157 offset:19456
	ds_read_b128 v[200:203], v157 offset:20480
	ds_read_b128 v[210:213], v157 offset:21504
	ds_read_b128 v[214:217], v157 offset:22528
	ds_read_b128 v[218:221], v157 offset:23552
	global_load_lds_dwordx4 v[204:205], off
	s_add_i32 m0, s63, 0x2000
	s_add_u32 s64, s34, 0x40000
	v_lshl_add_u64 v[222:223], s[34:35], 0, v[134:135]
	s_addc_u32 s65, s35, 0
	s_add_i32 s63, s53, s42
	global_load_lds_dwordx4 v[222:223], off
	v_lshl_add_u64 v[224:225], s[64:65], 0, v[130:131]
	s_mov_b32 m0, s63
	v_lshl_add_u64 v[226:227], s[36:37], 0, v[132:133]
	global_load_lds_dwordx4 v[224:225], off
	v_lshl_add_u64 v[224:225], s[64:65], 0, v[134:135]
	s_add_i32 m0, s63, 0x2000
	s_nop 0
	global_load_lds_dwordx4 v[224:225], off
	v_lshl_add_u64 v[224:225], s[36:37], 0, v[128:129]
	s_mov_b32 m0, s29
	s_nop 0
	global_load_lds_dwordx4 v[224:225], off
	s_mov_b32 m0, s43
	s_nop 0
	global_load_lds_dwordx4 v[226:227], off
	s_waitcnt vmcnt(8)
	s_waitcnt lgkmcnt(0)
	s_setprio 1
	s_barrier
	v_mfma_f32_16x16x32_bf16 v[60:63], v[144:147], v[184:187], v[60:63]
	v_mfma_f32_16x16x32_bf16 v[56:59], v[160:163], v[184:187], v[56:59]
	v_mfma_f32_16x16x32_bf16 v[44:47], v[144:147], v[192:195], v[44:47]
	v_mfma_f32_16x16x32_bf16 v[40:43], v[160:163], v[192:195], v[40:43]
	v_mfma_f32_16x16x32_bf16 v[28:31], v[144:147], v[200:203], v[28:31]
	v_mfma_f32_16x16x32_bf16 v[24:27], v[160:163], v[200:203], v[24:27]
	v_mfma_f32_16x16x32_bf16 v[12:15], v[144:147], v[214:217], v[12:15]
	v_mfma_f32_16x16x32_bf16 v[8:11], v[160:163], v[214:217], v[8:11]
	v_mfma_f32_16x16x32_bf16 v[60:63], v[148:151], v[188:191], v[60:63]
	v_mfma_f32_16x16x32_bf16 v[56:59], v[164:167], v[188:191], v[56:59]
	v_mfma_f32_16x16x32_bf16 v[44:47], v[148:151], v[196:199], v[44:47]
	v_mfma_f32_16x16x32_bf16 v[40:43], v[164:167], v[196:199], v[40:43]
	v_mfma_f32_16x16x32_bf16 v[28:31], v[148:151], v[210:213], v[28:31]
	v_mfma_f32_16x16x32_bf16 v[24:27], v[164:167], v[210:213], v[24:27]
	v_mfma_f32_16x16x32_bf16 v[12:15], v[148:151], v[218:221], v[12:15]
	v_mfma_f32_16x16x32_bf16 v[8:11], v[164:167], v[218:221], v[8:11]
	s_setprio 0
	s_setprio 1
	v_mfma_f32_16x16x32_bf16 v[52:55], v[168:171], v[184:187], v[52:55]
	v_mfma_f32_16x16x32_bf16 v[48:51], v[176:179], v[184:187], v[48:51]
	v_mfma_f32_16x16x32_bf16 v[36:39], v[168:171], v[192:195], v[36:39]
	v_mfma_f32_16x16x32_bf16 v[32:35], v[176:179], v[192:195], v[32:35]
	v_mfma_f32_16x16x32_bf16 v[20:23], v[168:171], v[200:203], v[20:23]
	v_mfma_f32_16x16x32_bf16 v[16:19], v[176:179], v[200:203], v[16:19]
	v_mfma_f32_16x16x32_bf16 v[4:7], v[168:171], v[214:217], v[4:7]
	v_mfma_f32_16x16x32_bf16 v[0:3], v[176:179], v[214:217], v[0:3]
	v_mfma_f32_16x16x32_bf16 v[52:55], v[172:175], v[188:191], v[52:55]
	v_mfma_f32_16x16x32_bf16 v[48:51], v[180:183], v[188:191], v[48:51]
	v_mfma_f32_16x16x32_bf16 v[36:39], v[172:175], v[196:199], v[36:39]
	v_mfma_f32_16x16x32_bf16 v[32:35], v[180:183], v[196:199], v[32:35]
	v_mfma_f32_16x16x32_bf16 v[20:23], v[172:175], v[210:213], v[20:23]
	v_mfma_f32_16x16x32_bf16 v[16:19], v[180:183], v[210:213], v[16:19]
	v_mfma_f32_16x16x32_bf16 v[4:7], v[172:175], v[218:221], v[4:7]
	v_mfma_f32_16x16x32_bf16 v[0:3], v[180:183], v[218:221], v[0:3]
	s_barrier
	s_setprio 0
	s_add_i32 s63, 0, 0x18000
	v_add_u32_e32 v159, s63, v153
	s_add_i32 s64, 0, 0x1c000
	ds_read_b128 v[144:147], v159
	ds_read_b128 v[148:151], v159 offset:1024
	ds_read_b128 v[160:163], v159 offset:2048
	ds_read_b128 v[164:167], v159 offset:3072
	v_add_u32_e32 v159, s64, v153
	ds_read_b128 v[168:171], v159
	ds_read_b128 v[172:175], v159 offset:1024
	ds_read_b128 v[176:179], v159 offset:2048
	ds_read_b128 v[180:183], v159 offset:3072
	s_add_u32 s36, s36, 0x40000
	s_addc_u32 s37, s37, 0
	s_mov_b32 m0, s44
	v_lshl_add_u64 v[228:229], s[36:37], 0, v[128:129]
	ds_read_b128 v[184:187], v157 offset:32768
	ds_read_b128 v[188:191], v157 offset:33792
	ds_read_b128 v[192:195], v157 offset:34816
	ds_read_b128 v[196:199], v157 offset:35840
	ds_read_b128 v[200:203], v157 offset:36864
	ds_read_b128 v[210:213], v157 offset:37888
	ds_read_b128 v[214:217], v157 offset:38912
	ds_read_b128 v[218:221], v157 offset:39936
	global_load_lds_dwordx4 v[228:229], off
	v_lshl_add_u64 v[228:229], s[36:37], 0, v[132:133]
	s_mov_b32 m0, s45
	s_nop 0
	global_load_lds_dwordx4 v[228:229], off
	s_waitcnt vmcnt(8)
	s_waitcnt lgkmcnt(0)
	s_setprio 1
	s_barrier
	v_mfma_f32_16x16x32_bf16 v[124:127], v[144:147], v[184:187], v[124:127]
	v_mfma_f32_16x16x32_bf16 v[120:123], v[160:163], v[184:187], v[120:123]
	v_mfma_f32_16x16x32_bf16 v[116:119], v[144:147], v[192:195], v[116:119]
	v_mfma_f32_16x16x32_bf16 v[104:107], v[160:163], v[192:195], v[104:107]
	v_mfma_f32_16x16x32_bf16 v[92:95], v[144:147], v[200:203], v[92:95]
	v_mfma_f32_16x16x32_bf16 v[88:91], v[160:163], v[200:203], v[88:91]
	v_mfma_f32_16x16x32_bf16 v[76:79], v[144:147], v[214:217], v[76:79]
	v_mfma_f32_16x16x32_bf16 v[72:75], v[160:163], v[214:217], v[72:75]
	v_mfma_f32_16x16x32_bf16 v[124:127], v[148:151], v[188:191], v[124:127]
	v_mfma_f32_16x16x32_bf16 v[120:123], v[164:167], v[188:191], v[120:123]
	v_mfma_f32_16x16x32_bf16 v[116:119], v[148:151], v[196:199], v[116:119]
	v_mfma_f32_16x16x32_bf16 v[104:107], v[164:167], v[196:199], v[104:107]
	v_mfma_f32_16x16x32_bf16 v[92:95], v[148:151], v[210:213], v[92:95]
	v_mfma_f32_16x16x32_bf16 v[88:91], v[164:167], v[210:213], v[88:91]
	v_mfma_f32_16x16x32_bf16 v[76:79], v[148:151], v[218:221], v[76:79]
	v_mfma_f32_16x16x32_bf16 v[72:75], v[164:167], v[218:221], v[72:75]
	s_setprio 0
	s_setprio 1
	v_mfma_f32_16x16x32_bf16 v[112:115], v[168:171], v[184:187], v[112:115]
	v_mfma_f32_16x16x32_bf16 v[108:111], v[176:179], v[184:187], v[108:111]
	v_mfma_f32_16x16x32_bf16 v[100:103], v[168:171], v[192:195], v[100:103]
	v_mfma_f32_16x16x32_bf16 v[96:99], v[176:179], v[192:195], v[96:99]
	v_mfma_f32_16x16x32_bf16 v[84:87], v[168:171], v[200:203], v[84:87]
	v_mfma_f32_16x16x32_bf16 v[80:83], v[176:179], v[200:203], v[80:83]
	v_mfma_f32_16x16x32_bf16 v[68:71], v[168:171], v[214:217], v[68:71]
	v_mfma_f32_16x16x32_bf16 v[64:67], v[176:179], v[214:217], v[64:67]
	v_mfma_f32_16x16x32_bf16 v[112:115], v[172:175], v[188:191], v[112:115]
	v_mfma_f32_16x16x32_bf16 v[108:111], v[180:183], v[188:191], v[108:111]
	v_mfma_f32_16x16x32_bf16 v[100:103], v[172:175], v[196:199], v[100:103]
	v_mfma_f32_16x16x32_bf16 v[96:99], v[180:183], v[196:199], v[96:99]
	v_mfma_f32_16x16x32_bf16 v[84:87], v[172:175], v[210:213], v[84:87]
	v_mfma_f32_16x16x32_bf16 v[80:83], v[180:183], v[210:213], v[80:83]
	v_mfma_f32_16x16x32_bf16 v[68:71], v[172:175], v[218:221], v[68:71]
	v_mfma_f32_16x16x32_bf16 v[64:67], v[180:183], v[218:221], v[64:67]
	s_barrier
	s_setprio 0
	s_add_i32 s36, s63, s42
	v_lshl_add_u64 v[204:205], v[204:205], 0, s[8:9]
	s_mov_b32 m0, s36
	ds_read_b128 v[184:187], v157 offset:49152
	ds_read_b128 v[188:191], v157 offset:50176
	ds_read_b128 v[192:195], v157 offset:51200
	ds_read_b128 v[196:199], v157 offset:52224
	ds_read_b128 v[200:203], v157 offset:53248
	ds_read_b128 v[210:213], v157 offset:54272
	ds_read_b128 v[214:217], v157 offset:55296
	ds_read_b128 v[218:221], v157 offset:56320
	global_load_lds_dwordx4 v[204:205], off
	s_add_i32 m0, s36, 0x2000
	s_add_u32 s34, s34, 0x40080
	v_lshl_add_u64 v[204:205], v[222:223], 0, s[8:9]
	s_addc_u32 s35, s35, 0
	s_add_i32 s36, s64, s42
	global_load_lds_dwordx4 v[204:205], off
	v_lshl_add_u64 v[204:205], s[34:35], 0, v[130:131]
	s_mov_b32 m0, s36
	s_nop 0
	global_load_lds_dwordx4 v[204:205], off
	v_lshl_add_u64 v[204:205], s[34:35], 0, v[134:135]
	s_add_i32 m0, s36, 0x2000
	s_nop 0
	global_load_lds_dwordx4 v[204:205], off
	v_lshl_add_u64 v[204:205], v[224:225], 0, s[8:9]
	s_mov_b32 m0, s49
	s_nop 0
	global_load_lds_dwordx4 v[204:205], off
	v_lshl_add_u64 v[204:205], v[226:227], 0, s[8:9]
	s_mov_b32 m0, s50
	s_nop 0
	global_load_lds_dwordx4 v[204:205], off
	s_waitcnt vmcnt(8)
	s_waitcnt lgkmcnt(0)
	s_setprio 1
	s_barrier
	v_mfma_f32_16x16x32_bf16 v[60:63], v[144:147], v[184:187], v[60:63]
	v_mfma_f32_16x16x32_bf16 v[56:59], v[160:163], v[184:187], v[56:59]
	v_mfma_f32_16x16x32_bf16 v[44:47], v[144:147], v[192:195], v[44:47]
	v_mfma_f32_16x16x32_bf16 v[40:43], v[160:163], v[192:195], v[40:43]
	v_mfma_f32_16x16x32_bf16 v[28:31], v[144:147], v[200:203], v[28:31]
	v_mfma_f32_16x16x32_bf16 v[24:27], v[160:163], v[200:203], v[24:27]
	v_mfma_f32_16x16x32_bf16 v[12:15], v[144:147], v[214:217], v[12:15]
	v_mfma_f32_16x16x32_bf16 v[8:11], v[160:163], v[214:217], v[8:11]
	v_mfma_f32_16x16x32_bf16 v[60:63], v[148:151], v[188:191], v[60:63]
	v_mfma_f32_16x16x32_bf16 v[56:59], v[164:167], v[188:191], v[56:59]
	v_mfma_f32_16x16x32_bf16 v[44:47], v[148:151], v[196:199], v[44:47]
	v_mfma_f32_16x16x32_bf16 v[40:43], v[164:167], v[196:199], v[40:43]
	v_mfma_f32_16x16x32_bf16 v[28:31], v[148:151], v[210:213], v[28:31]
	v_mfma_f32_16x16x32_bf16 v[24:27], v[164:167], v[210:213], v[24:27]
	v_mfma_f32_16x16x32_bf16 v[12:15], v[148:151], v[218:221], v[12:15]
	v_mfma_f32_16x16x32_bf16 v[8:11], v[164:167], v[218:221], v[8:11]
	s_setprio 0
	s_setprio 1
	v_mfma_f32_16x16x32_bf16 v[52:55], v[168:171], v[184:187], v[52:55]
	v_mfma_f32_16x16x32_bf16 v[48:51], v[176:179], v[184:187], v[48:51]
	v_mfma_f32_16x16x32_bf16 v[36:39], v[168:171], v[192:195], v[36:39]
	v_mfma_f32_16x16x32_bf16 v[32:35], v[176:179], v[192:195], v[32:35]
	v_mfma_f32_16x16x32_bf16 v[20:23], v[168:171], v[200:203], v[20:23]
	v_mfma_f32_16x16x32_bf16 v[16:19], v[176:179], v[200:203], v[16:19]
	v_mfma_f32_16x16x32_bf16 v[4:7], v[168:171], v[214:217], v[4:7]
	v_mfma_f32_16x16x32_bf16 v[0:3], v[176:179], v[214:217], v[0:3]
	v_mfma_f32_16x16x32_bf16 v[52:55], v[172:175], v[188:191], v[52:55]
	v_mfma_f32_16x16x32_bf16 v[48:51], v[180:183], v[188:191], v[48:51]
	v_mfma_f32_16x16x32_bf16 v[36:39], v[172:175], v[196:199], v[36:39]
	v_mfma_f32_16x16x32_bf16 v[32:35], v[180:183], v[196:199], v[32:35]
	v_mfma_f32_16x16x32_bf16 v[20:23], v[172:175], v[210:213], v[20:23]
	v_mfma_f32_16x16x32_bf16 v[16:19], v[180:183], v[210:213], v[16:19]
	v_mfma_f32_16x16x32_bf16 v[4:7], v[172:175], v[218:221], v[4:7]
	v_mfma_f32_16x16x32_bf16 v[0:3], v[180:183], v[218:221], v[0:3]
	s_barrier
	s_setprio 0
	s_add_i32 s62, s62, 2
	s_add_u32 s30, s30, 0x100
	s_addc_u32 s31, s31, 0
	s_add_u32 s60, s60, 0x100
	s_addc_u32 s61, s61, 0
	s_cmp_gt_u32 s62, 13
	s_cbranch_scc0 .LBB0_1310
	s_and_b64 vcc, exec, s[10:11]
	s_cbranch_vccz .LBB0_1313
	s_barrier

.LBB0_1389:
	ds_read_b128 v[128:131], v212
	ds_read_b128 v[132:135], v212 offset:1024
	ds_read_b128 v[136:139], v212 offset:2048
	ds_read_b128 v[140:143], v212 offset:3072
	ds_read_b128 v[144:147], v213
	ds_read_b128 v[148:151], v213 offset:1024
	ds_read_b128 v[152:155], v213 offset:2048
	ds_read_b128 v[156:159], v213 offset:3072
	s_add_u32 s30, s28, 0x100
	s_addc_u32 s31, s29, 0
	s_cmp_eq_u32 s56, 60
	s_cselect_b32 s37, s3, s31
	s_cselect_b32 s36, s19, s30
	s_cselect_b32 s35, s17, s55
	s_cselect_b32 s34, s25, s54
	v_lshl_add_u64 v[204:205], s[28:29], 0, v[180:181]
	s_add_i32 m0, s27, 0xc000
	ds_read_b128 v[160:163], v214
	ds_read_b128 v[164:167], v214 offset:1024
	ds_read_b128 v[168:171], v214 offset:2048
	ds_read_b128 v[172:175], v214 offset:3072
	ds_read_b128 v[188:191], v214 offset:4096
	ds_read_b128 v[192:195], v214 offset:5120
	ds_read_b128 v[196:199], v214 offset:6144
	ds_read_b128 v[200:203], v214 offset:7168
	global_load_lds_dwordx4 v[204:205], off
	v_lshl_add_u64 v[204:205], s[28:29], 0, v[182:183]
	s_add_i32 m0, s27, 0xe000
	s_nop 0
	global_load_lds_dwordx4 v[204:205], off
	s_waitcnt vmcnt(8)
	s_waitcnt lgkmcnt(0)
	s_setprio 1
	s_barrier
	v_mfma_f32_16x16x32_bf16 v[124:127], v[128:131], v[160:163], v[124:127]
	v_mfma_f32_16x16x32_bf16 v[120:123], v[136:139], v[160:163], v[120:123]
	v_mfma_f32_16x16x32_bf16 v[108:111], v[128:131], v[168:171], v[108:111]
	v_mfma_f32_16x16x32_bf16 v[104:107], v[136:139], v[168:171], v[104:107]
	v_mfma_f32_16x16x32_bf16 v[92:95], v[128:131], v[188:191], v[92:95]
	v_mfma_f32_16x16x32_bf16 v[88:91], v[136:139], v[188:191], v[88:91]
	v_mfma_f32_16x16x32_bf16 v[76:79], v[128:131], v[196:199], v[76:79]
	v_mfma_f32_16x16x32_bf16 v[72:75], v[136:139], v[196:199], v[72:75]
	v_mfma_f32_16x16x32_bf16 v[124:127], v[132:135], v[164:167], v[124:127]
	v_mfma_f32_16x16x32_bf16 v[120:123], v[140:143], v[164:167], v[120:123]
	v_mfma_f32_16x16x32_bf16 v[108:111], v[132:135], v[172:175], v[108:111]
	v_mfma_f32_16x16x32_bf16 v[104:107], v[140:143], v[172:175], v[104:107]
	v_mfma_f32_16x16x32_bf16 v[92:95], v[132:135], v[192:195], v[92:95]
	v_mfma_f32_16x16x32_bf16 v[88:91], v[140:143], v[192:195], v[88:91]
	v_mfma_f32_16x16x32_bf16 v[76:79], v[132:135], v[200:203], v[76:79]
	v_mfma_f32_16x16x32_bf16 v[72:75], v[140:143], v[200:203], v[72:75]
	s_setprio 0
	s_setprio 1
	v_mfma_f32_16x16x32_bf16 v[116:119], v[144:147], v[160:163], v[116:119]
	v_mfma_f32_16x16x32_bf16 v[112:115], v[152:155], v[160:163], v[112:115]
	v_mfma_f32_16x16x32_bf16 v[100:103], v[144:147], v[168:171], v[100:103]
	v_mfma_f32_16x16x32_bf16 v[96:99], v[152:155], v[168:171], v[96:99]
	v_mfma_f32_16x16x32_bf16 v[84:87], v[144:147], v[188:191], v[84:87]
	v_mfma_f32_16x16x32_bf16 v[80:83], v[152:155], v[188:191], v[80:83]
	v_mfma_f32_16x16x32_bf16 v[68:71], v[144:147], v[196:199], v[68:71]
	v_mfma_f32_16x16x32_bf16 v[64:67], v[152:155], v[196:199], v[64:67]
	v_mfma_f32_16x16x32_bf16 v[116:119], v[148:151], v[164:167], v[116:119]
	v_mfma_f32_16x16x32_bf16 v[112:115], v[156:159], v[164:167], v[112:115]
	v_mfma_f32_16x16x32_bf16 v[100:103], v[148:151], v[172:175], v[100:103]
	v_mfma_f32_16x16x32_bf16 v[96:99], v[156:159], v[172:175], v[96:99]
	v_mfma_f32_16x16x32_bf16 v[84:87], v[148:151], v[192:195], v[84:87]
	v_mfma_f32_16x16x32_bf16 v[80:83], v[156:159], v[192:195], v[80:83]
	v_mfma_f32_16x16x32_bf16 v[68:71], v[148:151], v[200:203], v[68:71]
	v_mfma_f32_16x16x32_bf16 v[64:67], v[156:159], v[200:203], v[64:67]
	s_barrier
	s_setprio 0
	s_add_i32 s28, s51, s40
	v_lshl_add_u64 v[204:205], s[34:35], 0, v[176:177]
	s_mov_b32 m0, s28
	ds_read_b128 v[160:163], v214 offset:16384
	ds_read_b128 v[164:167], v214 offset:17408
	ds_read_b128 v[168:171], v214 offset:18432
	ds_read_b128 v[172:175], v214 offset:19456
	ds_read_b128 v[188:191], v214 offset:20480
	ds_read_b128 v[192:195], v214 offset:21504
	ds_read_b128 v[196:199], v214 offset:22528
	ds_read_b128 v[200:203], v214 offset:23552
	global_load_lds_dwordx4 v[204:205], off
	s_add_i32 m0, s28, 0x2000
	s_add_u32 s28, s34, 0x100000
	v_lshl_add_u64 v[216:217], s[34:35], 0, v[178:179]
	s_addc_u32 s29, s35, 0
	s_add_i32 s57, s53, s40
	global_load_lds_dwordx4 v[216:217], off
	v_lshl_add_u64 v[218:219], s[28:29], 0, v[176:177]
	s_mov_b32 m0, s57
	v_lshl_add_u64 v[220:221], s[36:37], 0, v[178:179]
	global_load_lds_dwordx4 v[218:219], off
	v_lshl_add_u64 v[218:219], s[28:29], 0, v[178:179]
	s_add_i32 m0, s57, 0x2000
	s_nop 0
	global_load_lds_dwordx4 v[218:219], off
	v_lshl_add_u64 v[218:219], s[36:37], 0, v[176:177]
	s_mov_b32 m0, s27
	s_nop 0
	global_load_lds_dwordx4 v[218:219], off
	s_mov_b32 m0, s41
	s_nop 0
	global_load_lds_dwordx4 v[220:221], off
	s_waitcnt vmcnt(8)
	s_waitcnt lgkmcnt(0)
	s_setprio 1
	s_barrier
	v_mfma_f32_16x16x32_bf16 v[60:63], v[128:131], v[160:163], v[60:63]
	v_mfma_f32_16x16x32_bf16 v[56:59], v[136:139], v[160:163], v[56:59]
	v_mfma_f32_16x16x32_bf16 v[44:47], v[128:131], v[168:171], v[44:47]
	v_mfma_f32_16x16x32_bf16 v[40:43], v[136:139], v[168:171], v[40:43]
	v_mfma_f32_16x16x32_bf16 v[28:31], v[128:131], v[188:191], v[28:31]
	v_mfma_f32_16x16x32_bf16 v[24:27], v[136:139], v[188:191], v[24:27]
	v_mfma_f32_16x16x32_bf16 v[12:15], v[128:131], v[196:199], v[12:15]
	v_mfma_f32_16x16x32_bf16 v[8:11], v[136:139], v[196:199], v[8:11]
	v_mfma_f32_16x16x32_bf16 v[60:63], v[132:135], v[164:167], v[60:63]
	v_mfma_f32_16x16x32_bf16 v[56:59], v[140:143], v[164:167], v[56:59]
	v_mfma_f32_16x16x32_bf16 v[44:47], v[132:135], v[172:175], v[44:47]
	v_mfma_f32_16x16x32_bf16 v[40:43], v[140:143], v[172:175], v[40:43]
	v_mfma_f32_16x16x32_bf16 v[28:31], v[132:135], v[192:195], v[28:31]
	v_mfma_f32_16x16x32_bf16 v[24:27], v[140:143], v[192:195], v[24:27]
	v_mfma_f32_16x16x32_bf16 v[12:15], v[132:135], v[200:203], v[12:15]
	v_mfma_f32_16x16x32_bf16 v[8:11], v[140:143], v[200:203], v[8:11]
	s_setprio 0
	s_setprio 1
	v_mfma_f32_16x16x32_bf16 v[52:55], v[144:147], v[160:163], v[52:55]
	v_mfma_f32_16x16x32_bf16 v[48:51], v[152:155], v[160:163], v[48:51]
	v_mfma_f32_16x16x32_bf16 v[36:39], v[144:147], v[168:171], v[36:39]
	v_mfma_f32_16x16x32_bf16 v[32:35], v[152:155], v[168:171], v[32:35]
	v_mfma_f32_16x16x32_bf16 v[20:23], v[144:147], v[188:191], v[20:23]
	v_mfma_f32_16x16x32_bf16 v[16:19], v[152:155], v[188:191], v[16:19]
	v_mfma_f32_16x16x32_bf16 v[4:7], v[144:147], v[196:199], v[4:7]
	v_mfma_f32_16x16x32_bf16 v[0:3], v[152:155], v[196:199], v[0:3]
	v_mfma_f32_16x16x32_bf16 v[52:55], v[148:151], v[164:167], v[52:55]
	v_mfma_f32_16x16x32_bf16 v[48:51], v[156:159], v[164:167], v[48:51]
	v_mfma_f32_16x16x32_bf16 v[36:39], v[148:151], v[172:175], v[36:39]
	v_mfma_f32_16x16x32_bf16 v[32:35], v[156:159], v[172:175], v[32:35]
	v_mfma_f32_16x16x32_bf16 v[20:23], v[148:151], v[192:195], v[20:23]
	v_mfma_f32_16x16x32_bf16 v[16:19], v[156:159], v[192:195], v[16:19]
	v_mfma_f32_16x16x32_bf16 v[4:7], v[148:151], v[200:203], v[4:7]
	v_mfma_f32_16x16x32_bf16 v[0:3], v[156:159], v[200:203], v[0:3]
	s_barrier
	s_setprio 0
	s_add_i32 s57, 0, 0x18000
	s_add_i32 s58, 0, 0x1c000
	v_add_u32_e32 v140, s57, v210
	v_add_u32_e32 v156, s58, v210
	ds_read_b128 v[128:131], v140
	ds_read_b128 v[132:135], v140 offset:1024
	ds_read_b128 v[136:139], v140 offset:2048
	ds_read_b128 v[140:143], v140 offset:3072
	ds_read_b128 v[144:147], v156
	ds_read_b128 v[148:151], v156 offset:1024
	ds_read_b128 v[152:155], v156 offset:2048
	ds_read_b128 v[156:159], v156 offset:3072
	s_add_u32 s28, s36, 0x100000
	s_addc_u32 s29, s37, 0
	s_mov_b32 m0, s42
	v_lshl_add_u64 v[222:223], s[28:29], 0, v[176:177]
	ds_read_b128 v[160:163], v214 offset:32768
	ds_read_b128 v[164:167], v214 offset:33792
	ds_read_b128 v[168:171], v214 offset:34816
	ds_read_b128 v[172:175], v214 offset:35840
	ds_read_b128 v[188:191], v214 offset:36864
	ds_read_b128 v[192:195], v214 offset:37888
	ds_read_b128 v[196:199], v214 offset:38912
	ds_read_b128 v[200:203], v214 offset:39936
	global_load_lds_dwordx4 v[222:223], off
	v_lshl_add_u64 v[222:223], s[28:29], 0, v[178:179]
	s_mov_b32 m0, s43
	s_nop 0
	global_load_lds_dwordx4 v[222:223], off
	s_waitcnt vmcnt(8)
	s_waitcnt lgkmcnt(0)
	s_setprio 1
	s_barrier
	v_mfma_f32_16x16x32_bf16 v[124:127], v[128:131], v[160:163], v[124:127]
	v_mfma_f32_16x16x32_bf16 v[120:123], v[136:139], v[160:163], v[120:123]
	v_mfma_f32_16x16x32_bf16 v[108:111], v[128:131], v[168:171], v[108:111]
	v_mfma_f32_16x16x32_bf16 v[104:107], v[136:139], v[168:171], v[104:107]
	v_mfma_f32_16x16x32_bf16 v[92:95], v[128:131], v[188:191], v[92:95]
	v_mfma_f32_16x16x32_bf16 v[88:91], v[136:139], v[188:191], v[88:91]
	v_mfma_f32_16x16x32_bf16 v[76:79], v[128:131], v[196:199], v[76:79]
	v_mfma_f32_16x16x32_bf16 v[72:75], v[136:139], v[196:199], v[72:75]
	v_mfma_f32_16x16x32_bf16 v[124:127], v[132:135], v[164:167], v[124:127]
	v_mfma_f32_16x16x32_bf16 v[120:123], v[140:143], v[164:167], v[120:123]
	v_mfma_f32_16x16x32_bf16 v[108:111], v[132:135], v[172:175], v[108:111]
	v_mfma_f32_16x16x32_bf16 v[104:107], v[140:143], v[172:175], v[104:107]
	v_mfma_f32_16x16x32_bf16 v[92:95], v[132:135], v[192:195], v[92:95]
	v_mfma_f32_16x16x32_bf16 v[88:91], v[140:143], v[192:195], v[88:91]
	v_mfma_f32_16x16x32_bf16 v[76:79], v[132:135], v[200:203], v[76:79]
	v_mfma_f32_16x16x32_bf16 v[72:75], v[140:143], v[200:203], v[72:75]
	s_setprio 0
	s_setprio 1
	v_mfma_f32_16x16x32_bf16 v[116:119], v[144:147], v[160:163], v[116:119]
	v_mfma_f32_16x16x32_bf16 v[112:115], v[152:155], v[160:163], v[112:115]
	v_mfma_f32_16x16x32_bf16 v[100:103], v[144:147], v[168:171], v[100:103]
	v_mfma_f32_16x16x32_bf16 v[96:99], v[152:155], v[168:171], v[96:99]
	v_mfma_f32_16x16x32_bf16 v[84:87], v[144:147], v[188:191], v[84:87]
	v_mfma_f32_16x16x32_bf16 v[80:83], v[152:155], v[188:191], v[80:83]
	v_mfma_f32_16x16x32_bf16 v[68:71], v[144:147], v[196:199], v[68:71]
	v_mfma_f32_16x16x32_bf16 v[64:67], v[152:155], v[196:199], v[64:67]
	v_mfma_f32_16x16x32_bf16 v[116:119], v[148:151], v[164:167], v[116:119]
	v_mfma_f32_16x16x32_bf16 v[112:115], v[156:159], v[164:167], v[112:115]
	v_mfma_f32_16x16x32_bf16 v[100:103], v[148:151], v[172:175], v[100:103]
	v_mfma_f32_16x16x32_bf16 v[96:99], v[156:159], v[172:175], v[96:99]
	v_mfma_f32_16x16x32_bf16 v[84:87], v[148:151], v[192:195], v[84:87]
	v_mfma_f32_16x16x32_bf16 v[80:83], v[156:159], v[192:195], v[80:83]
	v_mfma_f32_16x16x32_bf16 v[68:71], v[148:151], v[200:203], v[68:71]
	v_mfma_f32_16x16x32_bf16 v[64:67], v[156:159], v[200:203], v[64:67]
	s_barrier
	s_setprio 0
	s_add_i32 s28, s57, s40
	v_lshl_add_u64 v[204:205], v[204:205], 0, s[12:13]
	s_mov_b32 m0, s28
	ds_read_b128 v[160:163], v214 offset:49152
	ds_read_b128 v[164:167], v214 offset:50176
	ds_read_b128 v[168:171], v214 offset:51200
	ds_read_b128 v[172:175], v214 offset:52224
	ds_read_b128 v[188:191], v214 offset:53248
	ds_read_b128 v[192:195], v214 offset:54272
	ds_read_b128 v[196:199], v214 offset:55296
	ds_read_b128 v[200:203], v214 offset:56320
	global_load_lds_dwordx4 v[204:205], off
	s_add_i32 m0, s28, 0x2000
	s_add_u32 s28, s34, 0x100080
	v_lshl_add_u64 v[204:205], v[216:217], 0, s[12:13]
	s_addc_u32 s29, s35, 0
	s_add_i32 s34, s58, s40
	global_load_lds_dwordx4 v[204:205], off
	v_lshl_add_u64 v[204:205], s[28:29], 0, v[176:177]
	s_mov_b32 m0, s34
	s_nop 0
	global_load_lds_dwordx4 v[204:205], off
	v_lshl_add_u64 v[204:205], s[28:29], 0, v[178:179]
	s_add_i32 m0, s34, 0x2000
	s_nop 0
	global_load_lds_dwordx4 v[204:205], off
	v_lshl_add_u64 v[204:205], v[218:219], 0, s[12:13]
	s_mov_b32 m0, s45
	s_nop 0
	global_load_lds_dwordx4 v[204:205], off
	v_lshl_add_u64 v[204:205], v[220:221], 0, s[12:13]
	s_mov_b32 m0, s48
	s_nop 0
	global_load_lds_dwordx4 v[204:205], off
	s_waitcnt vmcnt(8)
	s_waitcnt lgkmcnt(0)
	s_setprio 1
	s_barrier
	v_mfma_f32_16x16x32_bf16 v[60:63], v[128:131], v[160:163], v[60:63]
	v_mfma_f32_16x16x32_bf16 v[56:59], v[136:139], v[160:163], v[56:59]
	v_mfma_f32_16x16x32_bf16 v[44:47], v[128:131], v[168:171], v[44:47]
	v_mfma_f32_16x16x32_bf16 v[40:43], v[136:139], v[168:171], v[40:43]
	v_mfma_f32_16x16x32_bf16 v[28:31], v[128:131], v[188:191], v[28:31]
	v_mfma_f32_16x16x32_bf16 v[24:27], v[136:139], v[188:191], v[24:27]
	v_mfma_f32_16x16x32_bf16 v[12:15], v[128:131], v[196:199], v[12:15]
	v_mfma_f32_16x16x32_bf16 v[8:11], v[136:139], v[196:199], v[8:11]
	v_mfma_f32_16x16x32_bf16 v[60:63], v[132:135], v[164:167], v[60:63]
	v_mfma_f32_16x16x32_bf16 v[56:59], v[140:143], v[164:167], v[56:59]
	v_mfma_f32_16x16x32_bf16 v[44:47], v[132:135], v[172:175], v[44:47]
	v_mfma_f32_16x16x32_bf16 v[40:43], v[140:143], v[172:175], v[40:43]
	v_mfma_f32_16x16x32_bf16 v[28:31], v[132:135], v[192:195], v[28:31]
	v_mfma_f32_16x16x32_bf16 v[24:27], v[140:143], v[192:195], v[24:27]
	v_mfma_f32_16x16x32_bf16 v[12:15], v[132:135], v[200:203], v[12:15]
	v_mfma_f32_16x16x32_bf16 v[8:11], v[140:143], v[200:203], v[8:11]
	s_setprio 0
	s_setprio 1
	v_mfma_f32_16x16x32_bf16 v[52:55], v[144:147], v[160:163], v[52:55]
	v_mfma_f32_16x16x32_bf16 v[48:51], v[152:155], v[160:163], v[48:51]
	v_mfma_f32_16x16x32_bf16 v[36:39], v[144:147], v[168:171], v[36:39]
	v_mfma_f32_16x16x32_bf16 v[32:35], v[152:155], v[168:171], v[32:35]
	v_mfma_f32_16x16x32_bf16 v[20:23], v[144:147], v[188:191], v[20:23]
	v_mfma_f32_16x16x32_bf16 v[16:19], v[152:155], v[188:191], v[16:19]
	v_mfma_f32_16x16x32_bf16 v[4:7], v[144:147], v[196:199], v[4:7]
	v_mfma_f32_16x16x32_bf16 v[0:3], v[152:155], v[196:199], v[0:3]
	v_mfma_f32_16x16x32_bf16 v[52:55], v[148:151], v[164:167], v[52:55]
	v_mfma_f32_16x16x32_bf16 v[48:51], v[156:159], v[164:167], v[48:51]
	v_mfma_f32_16x16x32_bf16 v[36:39], v[148:151], v[172:175], v[36:39]
	v_mfma_f32_16x16x32_bf16 v[32:35], v[156:159], v[172:175], v[32:35]
	v_mfma_f32_16x16x32_bf16 v[20:23], v[148:151], v[192:195], v[20:23]
	v_mfma_f32_16x16x32_bf16 v[16:19], v[156:159], v[192:195], v[16:19]
	v_mfma_f32_16x16x32_bf16 v[4:7], v[148:151], v[200:203], v[4:7]
	v_mfma_f32_16x16x32_bf16 v[0:3], v[156:159], v[200:203], v[0:3]
	s_barrier
	s_setprio 0
	s_add_i32 s56, s56, 2
	s_add_u32 s54, s54, 0x100
	s_addc_u32 s55, s55, 0
	s_cmp_gt_u32 s56, 61
	s_mov_b64 s[28:29], s[30:31]
	s_cbranch_scc0 .LBB0_1389
	s_and_b64 vcc, exec, s[14:15]
	s_cbranch_vccz .LBB0_1392
	s_barrier
